# v12 + RG-LRU loops: exp pre-scale folded into fmamk, 1-a^2 clamp modifier instead of max(0,.) (128 fewer VALU per cb pair in both passes)
# speedup vs baseline: 1.0030x; 1.0030x over previous
.LBB0_709:
	v_add_u32_e32 v80, s11, v114
	v_add_u32_e32 v118, 16, v80
	v_add_u32_e32 v32, 0x210, v80
	v_ashrrev_i32_e32 v119, 31, v118
	v_ashrrev_i32_e32 v33, 31, v32
	v_lshlrev_b64 v[16:17], 7, v[118:119]
	v_lshlrev_b64 v[24:25], 7, v[32:33]
	v_lshlrev_b64 v[34:35], 2, v[118:119]
	v_add_u32_e32 v94, 0x410, v80
	v_add_u32_e32 v96, 0x610, v80
	v_lshl_add_u64 v[20:21], v[112:113], 0, v[16:17]
	v_lshl_add_u64 v[28:29], v[112:113], 0, v[24:25]
	v_lshl_add_u64 v[36:37], s[38:39], 0, v[34:35]
	v_lshl_add_u64 v[32:33], v[32:33], 2, s[38:39]
	v_ashrrev_i32_e32 v95, 31, v94
	v_ashrrev_i32_e32 v97, 31, v96
	global_load_dwordx4 v[16:19], v[20:21], off
	s_nop 0
	global_load_dwordx4 v[20:23], v[20:21], off offset:64
	s_nop 0
	global_load_dwordx4 v[24:27], v[28:29], off
	s_nop 0
	global_load_dwordx4 v[28:31], v[28:29], off offset:64
	v_lshlrev_b64 v[40:41], 7, v[96:97]
	global_load_dword v131, v[36:37], off
	global_load_dword v132, v[32:33], off
	v_lshlrev_b64 v[32:33], 7, v[94:95]
	v_lshl_add_u64 v[86:87], s[48:49], 0, v[34:35]
	v_lshl_add_u64 v[36:37], v[112:113], 0, v[32:33]
	v_lshl_add_u64 v[44:45], v[112:113], 0, v[40:41]
	v_lshl_add_u64 v[94:95], v[94:95], 2, s[38:39]
	global_load_dword v133, v[86:87], off
	global_load_dwordx4 v[32:35], v[36:37], off
	s_nop 0
	global_load_dwordx4 v[36:39], v[36:37], off offset:64
	s_nop 0
	global_load_dwordx4 v[40:43], v[44:45], off
	s_nop 0
	global_load_dwordx4 v[44:47], v[44:45], off offset:64
	s_waitcnt vmcnt(24) lgkmcnt(3)
	v_mfma_f32_16x16x32_bf16 v[100:103], v[0:3], v[64:67], 0
	global_load_dword v134, v[94:95], off
	v_lshl_add_u64 v[94:95], v[96:97], 2, s[38:39]
	global_load_dword v135, v[94:95], off
	global_load_dword v136, v[86:87], off offset:2048
	s_waitcnt lgkmcnt(1)
	v_mfma_f32_16x16x32_bf16 v[104:107], v[8:11], v[64:67], 0
	ds_read_u16 v85, v130
	ds_read_u16 v86, v130 offset:1024
	ds_read_u16 v88, v130 offset:2048
	ds_read_u16 v90, v130 offset:3072
	ds_read_u16 v93, v130 offset:4096
	ds_read_u16 v94, v130 offset:5120
	ds_read_u16 v95, v130 offset:6144
	ds_read_u16 v99, v130 offset:19456
	s_waitcnt lgkmcnt(8)
	ds_bpermute_b32 v81, v115, v121
	ds_bpermute_b32 v87, v115, v120
	ds_bpermute_b32 v96, v115, v122
	ds_bpermute_b32 v97, v115, v123
	s_waitcnt vmcnt(26)
	v_mfma_f32_16x16x32_bf16 v[64:67], v[4:7], v[72:75], v[100:103]
	ds_bpermute_b32 v98, v115, v124
	s_waitcnt lgkmcnt(12)
	v_lshlrev_b32_e32 v85, 16, v85
	s_waitcnt lgkmcnt(11)
	v_lshlrev_b32_e32 v86, 16, v86
	s_waitcnt vmcnt(25)
	v_mfma_f32_16x16x32_bf16 v[100:103], v[0:3], v[68:71], 0
	s_waitcnt lgkmcnt(3)
	v_fma_f32 v85, v81, v85, v87
	v_lshlrev_b32_e32 v88, 16, v88
	s_waitcnt lgkmcnt(2)
	v_fmac_f32_e32 v85, v96, v86
	v_mfma_f32_16x16x32_bf16 v[72:75], v[12:15], v[72:75], v[104:107]
	v_fma_f32 v86, v81, v86, v87
	v_lshlrev_b32_e32 v90, 16, v90
	s_waitcnt lgkmcnt(1)
	v_fmac_f32_e32 v85, v97, v88
	v_mfma_f32_16x16x32_bf16 v[104:107], v[8:11], v[68:71], 0
	v_fmac_f32_e32 v86, v96, v88
	v_fma_f32 v88, v81, v88, v87
	v_lshlrev_b32_e32 v93, 16, v93
	s_waitcnt vmcnt(24)
	v_mfma_f32_16x16x32_bf16 v[68:71], v[4:7], v[76:79], v[100:103]
	s_waitcnt lgkmcnt(0)
	v_fmac_f32_e32 v85, v98, v90
	v_fmac_f32_e32 v86, v97, v90
	v_fmac_f32_e32 v88, v96, v90
	s_waitcnt vmcnt(15)
	v_mfma_f32_16x16x32_bf16 v[100:103], v[0:3], v[48:51], 0
	v_fma_f32 v90, v81, v90, v87
	v_lshlrev_b32_e32 v94, 16, v94
	v_fmac_f32_e32 v86, v98, v93
	v_mfma_f32_16x16x32_bf16 v[76:79], v[12:15], v[76:79], v[104:107]
	v_fmac_f32_e32 v88, v97, v93
	v_fmac_f32_e32 v90, v96, v93
	ds_read_u16 v93, v130 offset:16384
	v_mfma_f32_16x16x32_bf16 v[104:107], v[8:11], v[48:51], 0
	v_lshlrev_b32_e32 v95, 16, v95
	v_fmac_f32_e32 v88, v98, v94
	v_fmac_f32_e32 v90, v97, v94
	v_mfma_f32_16x16x32_bf16 v[48:51], v[4:7], v[56:59], v[100:103]
	ds_read_u16 v94, v130 offset:17408
	v_fmac_f32_e32 v90, v98, v95
	ds_read_u16 v95, v130 offset:18432
	v_mfma_f32_16x16x32_bf16 v[100:103], v[0:3], v[52:55], 0
	v_mul_f32_e32 v92, 0xbfb8aa3b, v92
	v_mul_f32_e32 v91, 0xbfb8aa3b, v91
	v_fmamk_f32 v72, v72, 0xbfb8aa3b, v92
	v_fmamk_f32 v76, v76, 0xbfb8aa3b, v91
	v_exp_f32_e32 v72, v72
	v_exp_f32_e32 v76, v76
	v_mfma_f32_16x16x32_bf16 v[56:59], v[12:15], v[56:59], v[104:107]
	v_lshlrev_b32_e32 v99, 16, v99
	v_add_f32_e32 v72, 1.0, v72
	v_add_f32_e32 v76, 1.0, v76
	v_mfma_f32_16x16x32_bf16 v[104:107], v[8:11], v[52:55], 0
	v_fmamk_f32 v64, v64, 0xbfb8aa3b, v92
	v_mfma_f32_16x16x32_bf16 v[52:55], v[4:7], v[60:63], v[100:103]
	v_fmamk_f32 v68, v68, 0xbfb8aa3b, v91
	v_exp_f32_e32 v64, v64
	v_exp_f32_e32 v68, v68
	ds_read_u16 v100, v130 offset:20480
	ds_read_u16 v101, v130 offset:21504
	ds_read_u16 v102, v130 offset:22528
	s_waitcnt lgkmcnt(5)
	v_lshlrev_b32_e32 v93, 16, v93
	s_waitcnt lgkmcnt(4)
	v_lshlrev_b32_e32 v94, 16, v94
	v_fma_f32 v93, v81, v93, v87
	s_waitcnt lgkmcnt(3)
	v_lshlrev_b32_e32 v95, 16, v95
	v_fmac_f32_e32 v93, v96, v94
	v_fma_f32 v94, v81, v94, v87
	v_fmac_f32_e32 v93, v97, v95
	v_fmac_f32_e32 v94, v96, v95
	v_fma_f32 v95, v81, v95, v87
	v_fmac_f32_e32 v93, v98, v99
	v_fmac_f32_e32 v94, v97, v99
	v_fmac_f32_e32 v95, v96, v99
	v_fmac_f32_e32 v87, v81, v99
	v_mul_f32_e32 v99, v72, v76
	v_rcp_f32_e32 v99, v99
	v_fmamk_f32 v65, v65, 0xbfb8aa3b, v92
	v_mul_f32_e32 v76, v76, v99
	v_mul_f32_e32 v89, 0xbfb8aa3b, v89
	v_mul_f32_e32 v76, v76, v89
	v_exp_f32_e32 v76, v76
	v_fmamk_f32 v69, v69, 0xbfb8aa3b, v91
	v_exp_f32_e32 v65, v65
	v_exp_f32_e32 v69, v69
	v_fmamk_f32 v66, v66, 0xbfb8aa3b, v92
	v_fmamk_f32 v70, v70, 0xbfb8aa3b, v91
	v_add_f32_e32 v64, 1.0, v64
	v_add_f32_e32 v68, 1.0, v68
	v_fmamk_f32 v75, v75, 0xbfb8aa3b, v92
	v_fmamk_f32 v79, v79, 0xbfb8aa3b, v91
	v_fmamk_f32 v74, v74, 0xbfb8aa3b, v92
	v_fmamk_f32 v78, v78, 0xbfb8aa3b, v91
	v_fmamk_f32 v73, v73, 0xbfb8aa3b, v92
	v_fmamk_f32 v77, v77, 0xbfb8aa3b, v91
	v_mul_f32_e32 v72, v72, v99
	v_fma_f32 v99, -v76, v76, 1.0 clamp
	v_fmamk_f32 v67, v67, 0xbfb8aa3b, v92
	v_fmamk_f32 v71, v71, 0xbfb8aa3b, v91
	v_exp_f32_e32 v66, v66
	v_exp_f32_e32 v70, v70
	v_mul_f32_e32 v91, v64, v68
	s_waitcnt lgkmcnt(2)
	v_lshlrev_b32_e32 v100, 16, v100
	v_exp_f32_e32 v75, v75
	v_exp_f32_e32 v79, v79
	v_exp_f32_e32 v74, v74
	v_exp_f32_e32 v78, v78
	v_exp_f32_e32 v73, v73
	v_exp_f32_e32 v77, v77
	v_exp_f32_e32 v67, v67
	v_exp_f32_e32 v71, v71
	v_rcp_f32_e32 v91, v91
	s_waitcnt lgkmcnt(1)
	v_lshlrev_b32_e32 v101, 16, v101
	v_fmac_f32_e32 v95, v97, v100
	v_fmac_f32_e32 v87, v96, v100
	v_sqrt_f32_e32 v99, v99
	v_add_f32_e32 v65, 1.0, v65
	v_add_f32_e32 v69, 1.0, v69
	v_fmac_f32_e32 v95, v98, v101
	v_fmac_f32_e32 v87, v97, v101
	v_mul_f32_e32 v101, v65, v69
	v_add_f32_e32 v66, 1.0, v66
	v_add_f32_e32 v70, 1.0, v70
	v_rcp_f32_e32 v101, v101
	s_waitcnt lgkmcnt(0)
	v_lshlrev_b32_e32 v102, 16, v102
	v_fmac_f32_e32 v94, v98, v100
	v_add_f32_e32 v75, 1.0, v75
	v_add_f32_e32 v79, 1.0, v79
	v_add_f32_e32 v74, 1.0, v74
	v_add_f32_e32 v78, 1.0, v78
	v_add_f32_e32 v73, 1.0, v73
	v_add_f32_e32 v77, 1.0, v77
	v_mul_f32_e32 v72, v72, v93
	v_add_f32_e32 v67, 1.0, v67
	v_add_f32_e32 v71, 1.0, v71
	v_mul_f32_e32 v100, v66, v70
	v_mul_f32_e32 v68, v68, v91
	v_fmac_f32_e32 v87, v98, v102
	v_mul_f32_e32 v96, v75, v79
	v_mul_f32_e32 v97, v74, v78
	v_mul_f32_e32 v98, v73, v77
	v_mul_f32_e32 v72, v99, v72
	v_mul_f32_e32 v99, v67, v71
	v_rcp_f32_e32 v100, v100
	v_mul_f32_e32 v68, v68, v89
	v_rcp_f32_e32 v96, v96
	v_rcp_f32_e32 v97, v97
	v_rcp_f32_e32 v98, v98
	v_rcp_f32_e32 v99, v99
	v_mul_f32_e32 v69, v69, v101
	v_exp_f32_e32 v68, v68
	v_mul_f32_e32 v69, v69, v89
	v_mul_f32_e32 v70, v70, v100
	v_mul_f32_e32 v79, v79, v96
	v_mul_f32_e32 v78, v78, v97
	v_mul_f32_e32 v77, v77, v98
	v_mul_f32_e32 v71, v71, v99
	v_mul_f32_e32 v70, v70, v89
	v_exp_f32_e32 v69, v69
	v_mul_f32_e32 v79, v79, v89
	v_mul_f32_e32 v78, v78, v89
	v_mul_f32_e32 v77, v77, v89
	v_mul_f32_e32 v71, v71, v89
	v_fma_f32 v89, -v68, v68, 1.0 clamp
	v_exp_f32_e32 v70, v70
	v_sqrt_f32_e32 v89, v89
	v_exp_f32_e32 v71, v71
	v_mul_f32_e32 v65, v65, v101
	v_fma_f32 v101, -v69, v69, 1.0 clamp
	v_mul_f32_e32 v64, v64, v91
	v_mul_f32_e32 v66, v66, v100
	v_fma_f32 v100, -v70, v70, 1.0 clamp
	v_sqrt_f32_e32 v101, v101
	v_mul_f32_e32 v64, v64, v85
	v_mul_f32_e32 v64, v89, v64
	v_mul_f32_e32 v67, v67, v99
	v_fma_f32 v99, -v71, v71, 1.0 clamp
	v_sqrt_f32_e32 v100, v100
	v_fmac_f32_e32 v64, 0, v68
	v_mul_f32_e32 v65, v65, v86
	v_mul_f32_e32 v64, v69, v64
	v_sqrt_f32_e32 v99, v99
	v_fmac_f32_e32 v64, v101, v65
	v_mul_f32_e32 v66, v66, v88
	v_mul_f32_e32 v64, v70, v64
	v_mul_f32_e32 v65, v68, v69
	v_fmac_f32_e32 v64, v100, v66
	v_mul_f32_e32 v67, v67, v90
	v_mul_f32_e32 v65, v70, v65
	v_mul_f32_e32 v64, v71, v64
	v_fmac_f32_e32 v64, v99, v67
	v_mul_f32_e32 v65, v71, v65
	ds_bpermute_b32 v66, v128, v65
	ds_bpermute_b32 v67, v128, v64
	v_exp_f32_e32 v77, v77
	s_waitcnt lgkmcnt(1)
	v_mul_f32_e32 v66, v65, v66
	s_waitcnt lgkmcnt(0)
	v_fma_f32 v67, v65, v67, v64
	v_exp_f32_e32 v78, v78
	v_cndmask_b32_e64 v64, v67, v64, s[44:45]
	v_cndmask_b32_e64 v65, v66, v65, s[44:45]
	ds_bpermute_b32 v66, v126, v65
	ds_bpermute_b32 v67, v126, v64
	v_exp_f32_e32 v79, v79
	v_mul_f32_e32 v73, v73, v98
	v_fma_f32 v98, -v77, v77, 1.0 clamp
	v_mul_f32_e32 v74, v74, v97
	v_fma_f32 v97, -v78, v78, 1.0 clamp
	v_sqrt_f32_e32 v98, v98
	v_mul_f32_e32 v75, v75, v96
	v_fma_f32 v96, -v79, v79, 1.0 clamp
	v_sqrt_f32_e32 v97, v97
	s_waitcnt lgkmcnt(0)
	v_fma_f32 v67, v65, v67, v64
	v_mul_f32_e32 v66, v65, v66
	v_fmac_f32_e32 v72, 0, v76
	v_mul_f32_e32 v73, v73, v94
	v_cndmask_b32_e64 v67, v64, v67, s[46:47]
	v_cndmask_b32_e64 v64, v65, v66, s[46:47]
	v_mul_f32_e32 v65, v77, v72
	v_sqrt_f32_e32 v96, v96
	v_fmac_f32_e32 v65, v98, v73
	v_mul_f32_e32 v74, v74, v95
	v_mul_f32_e32 v65, v78, v65
	ds_bpermute_b32 v66, v129, v67
	v_mul_f32_e32 v67, v76, v77
	v_fmac_f32_e32 v65, v97, v74
	v_mul_f32_e32 v75, v75, v87
	v_mul_f32_e32 v67, v78, v67
	v_mul_f32_e32 v65, v79, v65
	v_fmac_f32_e32 v65, v96, v75
	v_mul_f32_e32 v67, v79, v67
	ds_bpermute_b32 v68, v128, v67
	ds_bpermute_b32 v69, v128, v65
	ds_bpermute_b32 v64, v129, v64
	v_mfma_f32_16x16x32_bf16 v[60:63], v[12:15], v[60:63], v[104:107]
	v_ashrrev_i32_e32 v81, 31, v80
	s_waitcnt lgkmcnt(2)
	v_mul_f32_e32 v68, v67, v68
	s_waitcnt lgkmcnt(1)
	v_fma_f32 v69, v67, v69, v65
	v_cndmask_b32_e64 v65, v69, v65, s[44:45]
	v_cndmask_b32_e64 v67, v68, v67, s[44:45]
	ds_bpermute_b32 v68, v126, v67
	ds_bpermute_b32 v69, v126, v65
	s_waitcnt lgkmcnt(1)
	v_mul_f32_e32 v68, v67, v68
	s_waitcnt lgkmcnt(0)
	v_fma_f32 v69, v67, v69, v65
	v_cndmask_b32_e64 v65, v65, v69, s[46:47]
	v_cndmask_b32_e64 v67, v67, v68, s[46:47]
	ds_bpermute_b32 v67, v129, v67
	ds_bpermute_b32 v65, v129, v65
	s_and_saveexec_b64 s[4:5], s[44:45]
	s_cbranch_execz .LBB0_711
	s_waitcnt lgkmcnt(0)
	v_fmac_f32_e32 v65, v66, v67
	v_mul_f32_e32 v64, v64, v67
	v_lshl_add_u64 v[66:67], v[80:81], 3, s[58:59]
	global_store_dwordx2 v[66:67], v[64:65], off
.LBB0_711:
	s_or_b64 exec, exec, s[4:5]
	v_mul_f32_e32 v84, 0xbfb8aa3b, v84
	v_mul_f32_e32 v83, 0xbfb8aa3b, v83
	v_fmamk_f32 v51, v51, 0xbfb8aa3b, v84
	v_fmamk_f32 v55, v55, 0xbfb8aa3b, v83
	v_exp_f32_e32 v51, v51
	v_exp_f32_e32 v55, v55
	v_add_f32_e32 v51, 1.0, v51
	v_add_f32_e32 v55, 1.0, v55
	s_waitcnt lgkmcnt(1)
	v_mul_f32_e32 v67, v51, v55
	v_rcp_f32_e32 v67, v67
	v_fmamk_f32 v50, v50, 0xbfb8aa3b, v84
	v_fmamk_f32 v54, v54, 0xbfb8aa3b, v83
	v_exp_f32_e32 v50, v50
	v_mul_f32_e32 v55, v55, v67
	s_waitcnt vmcnt(14)
	v_mul_f32_e32 v82, 0xbfb8aa3b, v82
	v_mul_f32_e32 v55, v55, v82
	v_exp_f32_e32 v55, v55
	v_mul_f32_e32 v51, v51, v67
	v_exp_f32_e32 v54, v54
	v_mul_f32_e32 v51, v51, v90
	v_fma_f32 v67, -v55, v55, 1.0 clamp
	v_sqrt_f32_e32 v67, v67
	v_add_f32_e32 v50, 1.0, v50
	v_add_f32_e32 v54, 1.0, v54
	v_mul_f32_e32 v51, v51, v67
	v_mul_f32_e32 v67, v50, v54
	v_rcp_f32_e32 v67, v67
	v_fmamk_f32 v49, v49, 0xbfb8aa3b, v84
	v_mul_f32_e32 v50, v50, v67
	v_mul_f32_e32 v68, v50, v88
	v_mul_f32_e32 v50, v54, v67
	v_mul_f32_e32 v50, v50, v82
	v_exp_f32_e32 v54, v50
	v_exp_f32_e32 v49, v49
	v_fmamk_f32 v59, v59, 0xbfb8aa3b, v84
	v_fmamk_f32 v63, v63, 0xbfb8aa3b, v83
	v_fma_f32 v50, -v54, v54, 1.0 clamp
	v_sqrt_f32_e32 v67, v50
	v_fmamk_f32 v50, v53, 0xbfb8aa3b, v83
	v_exp_f32_e32 v50, v50
	v_exp_f32_e32 v59, v59
	v_exp_f32_e32 v63, v63
	v_add_f32_e32 v49, 1.0, v49
	v_add_f32_e32 v50, 1.0, v50
	v_mul_f32_e32 v53, v49, v50
	v_add_f32_e32 v59, 1.0, v59
	v_add_f32_e32 v63, 1.0, v63
	v_rcp_f32_e32 v53, v53
	v_mul_f32_e32 v64, v59, v63
	v_rcp_f32_e32 v64, v64
	v_mul_f32_e32 v50, v50, v53
	v_mul_f32_e32 v50, v50, v82
	v_mul_f32_e32 v59, v59, v64
	s_waitcnt lgkmcnt(0)
	v_mul_f32_e32 v65, v59, v87
	v_mul_f32_e32 v59, v63, v64
	v_mul_f32_e32 v49, v49, v53
	v_exp_f32_e32 v53, v50
	v_mul_f32_e32 v59, v59, v82
	v_exp_f32_e32 v59, v59
	v_fma_f32 v50, -v53, v53, 1.0 clamp
	v_fmamk_f32 v58, v58, 0xbfb8aa3b, v84
	v_fmamk_f32 v62, v62, 0xbfb8aa3b, v83
	v_exp_f32_e32 v58, v58
	v_exp_f32_e32 v62, v62
	v_sqrt_f32_e32 v69, v50
	v_fma_f32 v63, -v59, v59, 1.0 clamp
	v_fmamk_f32 v57, v57, 0xbfb8aa3b, v84
	v_fmamk_f32 v61, v61, 0xbfb8aa3b, v83
	v_fmamk_f32 v48, v48, 0xbfb8aa3b, v84
	v_fmamk_f32 v50, v52, 0xbfb8aa3b, v83
	v_exp_f32_e32 v57, v57
	v_exp_f32_e32 v61, v61
	v_exp_f32_e32 v48, v48
	v_exp_f32_e32 v50, v50
	v_sqrt_f32_e32 v63, v63
	v_fmamk_f32 v56, v56, 0xbfb8aa3b, v84
	v_fmamk_f32 v60, v60, 0xbfb8aa3b, v83
	v_add_f32_e32 v58, 1.0, v58
	v_add_f32_e32 v62, 1.0, v62
	v_exp_f32_e32 v56, v56
	v_exp_f32_e32 v60, v60
	v_mul_f32_e32 v64, v58, v62
	v_rcp_f32_e32 v64, v64
	v_add_f32_e32 v57, 1.0, v57
	v_add_f32_e32 v61, 1.0, v61
	v_add_f32_e32 v48, 1.0, v48
	v_add_f32_e32 v50, 1.0, v50
	v_mul_f32_e32 v63, v63, v65
	v_mul_f32_e32 v65, v57, v61
	v_mul_f32_e32 v52, v48, v50
	v_rcp_f32_e32 v65, v65
	v_add_f32_e32 v56, 1.0, v56
	v_add_f32_e32 v60, 1.0, v60
	v_rcp_f32_e32 v52, v52
	v_mul_f32_e32 v66, v56, v60
	v_mul_f32_e32 v62, v62, v64
	v_rcp_f32_e32 v66, v66
	v_mul_f32_e32 v62, v62, v82
	v_mul_f32_e32 v61, v61, v65
	v_mul_f32_e32 v48, v48, v52
	v_exp_f32_e32 v62, v62
	v_mul_f32_e32 v61, v61, v82
	v_mul_f32_e32 v70, v48, v85
	v_mul_f32_e32 v48, v50, v52
	v_mul_f32_e32 v60, v60, v66
	v_mul_f32_e32 v48, v48, v82
	v_exp_f32_e32 v61, v61
	v_mul_f32_e32 v60, v60, v82
	v_exp_f32_e32 v52, v48
	v_mul_f32_e32 v58, v58, v64
	v_fma_f32 v64, -v62, v62, 1.0 clamp
	v_exp_f32_e32 v60, v60
	v_sqrt_f32_e32 v64, v64
	v_mul_f32_e32 v57, v57, v65
	v_fma_f32 v65, -v61, v61, 1.0 clamp
	v_fma_f32 v48, -v52, v52, 1.0 clamp
	v_sqrt_f32_e32 v65, v65
	v_mul_f32_e32 v56, v56, v66
	v_fma_f32 v66, -v60, v60, 1.0 clamp
	v_fmac_f32_e32 v63, 0, v59
	v_fmac_f32_e32 v51, 0, v55
	v_mul_f32_e32 v58, v58, v95
	v_sqrt_f32_e32 v71, v48
	v_mul_f32_e32 v48, v62, v63
	v_mul_f32_e32 v51, v54, v51
	v_sqrt_f32_e32 v66, v66
	v_fmac_f32_e32 v48, v64, v58
	v_fmac_f32_e32 v51, v68, v67
	v_mul_f32_e32 v57, v57, v94
	v_mul_f32_e32 v49, v49, v86
	v_mul_f32_e32 v48, v61, v48
	v_mul_f32_e32 v51, v53, v51
	v_mul_f32_e32 v50, v59, v62
	v_fmac_f32_e32 v48, v65, v57
	v_mul_f32_e32 v54, v55, v54
	v_fmac_f32_e32 v51, v49, v69
	v_mul_f32_e32 v56, v56, v93
	v_mul_f32_e32 v50, v61, v50
	v_mul_f32_e32 v48, v60, v48
	v_mul_f32_e32 v49, v53, v54
	v_mul_f32_e32 v51, v52, v51
	v_fmac_f32_e32 v48, v66, v56
	v_mul_f32_e32 v50, v60, v50
	v_fmac_f32_e32 v51, v70, v71
	v_mul_f32_e32 v49, v52, v49
	ds_bpermute_b32 v56, v125, v50
	ds_bpermute_b32 v57, v125, v48
	ds_bpermute_b32 v52, v125, v49
	ds_bpermute_b32 v53, v125, v51
	s_waitcnt lgkmcnt(3)
	v_mul_f32_e32 v56, v50, v56
	s_waitcnt lgkmcnt(2)
	v_fma_f32 v57, v50, v57, v48
	s_waitcnt lgkmcnt(1)
	v_mul_f32_e32 v52, v49, v52
	s_waitcnt lgkmcnt(0)
	v_fma_f32 v53, v49, v53, v51
	v_cndmask_b32_e64 v48, v57, v48, s[40:41]
	v_cndmask_b32_e64 v50, v56, v50, s[40:41]
	v_cndmask_b32_e64 v51, v53, v51, s[40:41]
	v_cndmask_b32_e64 v49, v52, v49, s[40:41]
	ds_bpermute_b32 v56, v126, v50
	ds_bpermute_b32 v57, v126, v48
	ds_bpermute_b32 v52, v126, v49
	ds_bpermute_b32 v53, v126, v51
	s_waitcnt lgkmcnt(3)
	v_mul_f32_e32 v56, v50, v56
	s_waitcnt lgkmcnt(2)
	v_fma_f32 v57, v50, v57, v48
	s_waitcnt lgkmcnt(1)
	v_mul_f32_e32 v52, v49, v52
	s_waitcnt lgkmcnt(0)
	v_fma_f32 v53, v49, v53, v51
	v_cndmask_b32_e64 v57, v48, v57, s[42:43]
	v_cndmask_b32_e64 v48, v50, v56, s[42:43]
	v_cndmask_b32_e64 v53, v51, v53, s[42:43]
	v_cndmask_b32_e64 v49, v49, v52, s[42:43]
	ds_bpermute_b32 v48, v127, v48
	ds_bpermute_b32 v50, v127, v57
	ds_bpermute_b32 v51, v127, v49
	ds_bpermute_b32 v49, v127, v53
	s_and_saveexec_b64 s[4:5], s[44:45]
	s_cbranch_execz .LBB0_713
	v_lshl_add_u64 v[52:53], v[80:81], 3, s[60:61]
	s_waitcnt lgkmcnt(0)
	v_fmac_f32_e32 v49, v50, v51
	v_mul_f32_e32 v48, v48, v51
	global_store_dwordx2 v[52:53], v[48:49], off

.LBB0_715:
	ds_read_u16 v143, v130 offset:32
	ds_read_u16 v144, v130 offset:1056
	ds_read_u16 v145, v130 offset:2080
	ds_read_u16 v146, v130 offset:3104
	ds_read_u16 v148, v130 offset:4128
	ds_read_u16 v149, v130 offset:5152
	ds_read_u16 v150, v130 offset:6176
	ds_read_u16 v155, v130 offset:19488
	ds_bpermute_b32 v151, v115, v121 offset:64
	ds_bpermute_b32 v147, v115, v120 offset:64
	ds_bpermute_b32 v152, v115, v122 offset:64
	v_mfma_f32_16x16x32_bf16 v[84:87], v[8:11], v[16:19], 0
	ds_bpermute_b32 v153, v115, v123 offset:64
	ds_bpermute_b32 v154, v115, v124 offset:64
	s_waitcnt lgkmcnt(12)
	v_lshlrev_b32_e32 v143, 16, v143
	v_mfma_f32_16x16x32_bf16 v[104:107], v[12:15], v[20:23], v[84:87]
	s_waitcnt lgkmcnt(11)
	v_lshlrev_b32_e32 v144, 16, v144
	s_waitcnt lgkmcnt(3)
	v_fma_f32 v143, v151, v143, v147
	v_lshlrev_b32_e32 v145, 16, v145
	v_mfma_f32_16x16x32_bf16 v[84:87], v[8:11], v[24:27], 0
	s_waitcnt lgkmcnt(2)
	v_fmac_f32_e32 v143, v152, v144
	v_fma_f32 v144, v151, v144, v147
	v_lshlrev_b32_e32 v146, 16, v146
	s_waitcnt lgkmcnt(1)
	v_fmac_f32_e32 v143, v153, v145
	v_fmac_f32_e32 v144, v152, v145
	v_fma_f32 v145, v151, v145, v147
	v_lshlrev_b32_e32 v148, 16, v148
	s_waitcnt lgkmcnt(0)
	v_fmac_f32_e32 v143, v154, v146
	v_fmac_f32_e32 v144, v153, v146
	v_fmac_f32_e32 v145, v152, v146
	v_fma_f32 v146, v151, v146, v147
	v_mfma_f32_16x16x32_bf16 v[108:111], v[12:15], v[28:31], v[84:87]
	v_lshlrev_b32_e32 v149, 16, v149
	v_fmac_f32_e32 v144, v154, v148
	v_fmac_f32_e32 v145, v153, v148
	v_fmac_f32_e32 v146, v152, v148
	ds_read_u16 v148, v130 offset:16416
	ds_read_u16 v156, v130 offset:20512
	ds_read_u16 v157, v130 offset:21536
	ds_read_u16 v158, v130 offset:22560
	v_lshlrev_b32_e32 v150, 16, v150
	v_fmac_f32_e32 v145, v154, v149
	v_fmac_f32_e32 v146, v153, v149
	ds_read_u16 v149, v130 offset:17440
	v_fmac_f32_e32 v146, v154, v150
	ds_read_u16 v150, v130 offset:18464
	v_mfma_f32_16x16x32_bf16 v[80:83], v[0:3], v[16:19], 0
	v_mul_f32_e32 v131, 0xbfb8aa3b, v131
	v_mul_f32_e32 v132, 0xbfb8aa3b, v132
	s_waitcnt lgkmcnt(5)
	v_lshlrev_b32_e32 v148, 16, v148
	v_fmamk_f32 v104, v104, 0xbfb8aa3b, v131
	v_fmamk_f32 v108, v108, 0xbfb8aa3b, v132
	s_waitcnt lgkmcnt(1)
	v_lshlrev_b32_e32 v149, 16, v149
	v_fma_f32 v148, v151, v148, v147
	v_exp_f32_e32 v104, v104
	v_exp_f32_e32 v108, v108
	v_mfma_f32_16x16x32_bf16 v[96:99], v[4:7], v[20:23], v[80:83]
	s_waitcnt lgkmcnt(0)
	v_lshlrev_b32_e32 v150, 16, v150
	v_lshlrev_b32_e32 v155, 16, v155
	v_fmac_f32_e32 v148, v152, v149
	v_mfma_f32_16x16x32_bf16 v[80:83], v[0:3], v[24:27], 0
	v_fma_f32 v149, v151, v149, v147
	v_lshlrev_b32_e32 v156, 16, v156
	v_fmac_f32_e32 v148, v153, v150
	v_fmac_f32_e32 v149, v152, v150
	v_fma_f32 v150, v151, v150, v147
	v_fmac_f32_e32 v147, v151, v155
	v_lshlrev_b32_e32 v157, 16, v157
	v_fmac_f32_e32 v150, v152, v155
	v_fmac_f32_e32 v147, v152, v156
	v_lshlrev_b32_e32 v158, 16, v158
	v_fmac_f32_e32 v149, v153, v155
	v_fmac_f32_e32 v150, v153, v156
	v_fmac_f32_e32 v147, v153, v157
	v_add_f32_e32 v104, 1.0, v104
	v_add_f32_e32 v108, 1.0, v108
	v_mfma_f32_16x16x32_bf16 v[100:103], v[4:7], v[28:31], v[80:83]
	v_fmac_f32_e32 v148, v154, v155
	v_fmac_f32_e32 v149, v154, v156
	v_fmac_f32_e32 v150, v154, v157
	v_fmac_f32_e32 v147, v154, v158
	v_mul_f32_e32 v154, v104, v108
	v_rcp_f32_e32 v154, v154
	s_nop 0
	v_fmamk_f32 v96, v96, 0xbfb8aa3b, v131
	v_mul_f32_e32 v108, v108, v154
	v_fmamk_f32 v100, v100, 0xbfb8aa3b, v132
	v_mul_f32_e32 v133, 0xbfb8aa3b, v133
	v_mul_f32_e32 v108, v108, v133
	v_exp_f32_e32 v96, v96
	v_exp_f32_e32 v100, v100
	v_exp_f32_e32 v108, v108
	v_fmamk_f32 v97, v97, 0xbfb8aa3b, v131
	v_fmamk_f32 v101, v101, 0xbfb8aa3b, v132
	v_exp_f32_e32 v97, v97
	v_exp_f32_e32 v101, v101
	v_fmamk_f32 v98, v98, 0xbfb8aa3b, v131
	v_fmamk_f32 v102, v102, 0xbfb8aa3b, v132
	v_add_f32_e32 v96, 1.0, v96
	v_add_f32_e32 v100, 1.0, v100
	v_exp_f32_e32 v98, v98
	v_exp_f32_e32 v102, v102
	v_mul_f32_e32 v157, v96, v100
	v_mul_f32_e32 v104, v104, v154
	v_fma_f32 v154, -v108, v108, 1.0 clamp
	v_fmamk_f32 v99, v99, 0xbfb8aa3b, v131
	v_fmamk_f32 v103, v103, 0xbfb8aa3b, v132
	v_rcp_f32_e32 v157, v157
	v_exp_f32_e32 v99, v99
	v_exp_f32_e32 v103, v103
	v_add_f32_e32 v97, 1.0, v97
	v_add_f32_e32 v101, 1.0, v101
	v_sqrt_f32_e32 v154, v154
	v_mul_f32_e32 v156, v97, v101
	v_add_f32_e32 v98, 1.0, v98
	v_add_f32_e32 v102, 1.0, v102
	v_rcp_f32_e32 v156, v156
	v_mul_f32_e32 v155, v98, v102
	v_mul_f32_e32 v100, v100, v157
	v_mul_f32_e32 v104, v104, v148
	v_add_f32_e32 v99, 1.0, v99
	v_add_f32_e32 v103, 1.0, v103
	v_rcp_f32_e32 v155, v155
	v_mul_f32_e32 v100, v100, v133
	v_mul_f32_e32 v104, v154, v104
	v_mul_f32_e32 v154, v99, v103
	v_rcp_f32_e32 v154, v154
	v_mul_f32_e32 v101, v101, v156
	v_exp_f32_e32 v100, v100
	v_mul_f32_e32 v101, v101, v133
	v_mul_f32_e32 v102, v102, v155
	v_mul_f32_e32 v102, v102, v133
	v_exp_f32_e32 v101, v101
	v_mul_f32_e32 v103, v103, v154
	v_mul_f32_e32 v96, v96, v157
	v_fma_f32 v157, -v100, v100, 1.0 clamp
	v_mul_f32_e32 v103, v103, v133
	v_exp_f32_e32 v102, v102
	v_sqrt_f32_e32 v157, v157
	v_exp_f32_e32 v103, v103
	v_mul_f32_e32 v97, v97, v156
	v_fma_f32 v156, -v101, v101, 1.0 clamp
	v_fmamk_f32 v105, v105, 0xbfb8aa3b, v131
	v_fmamk_f32 v109, v109, 0xbfb8aa3b, v132
	v_exp_f32_e32 v105, v105
	v_exp_f32_e32 v109, v109
	v_mul_f32_e32 v98, v98, v155
	v_fma_f32 v155, -v102, v102, 1.0 clamp
	v_sqrt_f32_e32 v156, v156
	v_mul_f32_e32 v96, v96, v143
	v_fmamk_f32 v106, v106, 0xbfb8aa3b, v131
	v_fmamk_f32 v110, v110, 0xbfb8aa3b, v132
	v_mul_f32_e32 v96, v157, v96
	v_exp_f32_e32 v106, v106
	v_exp_f32_e32 v110, v110
	v_mul_f32_e32 v99, v99, v154
	v_fma_f32 v154, -v103, v103, 1.0 clamp
	v_sqrt_f32_e32 v155, v155
	v_fmac_f32_e32 v96, 0, v100
	v_fmamk_f32 v107, v107, 0xbfb8aa3b, v131
	v_fmamk_f32 v111, v111, 0xbfb8aa3b, v132
	v_mul_f32_e32 v97, v97, v144
	v_mul_f32_e32 v96, v101, v96
	v_exp_f32_e32 v107, v107
	v_exp_f32_e32 v111, v111
	v_add_f32_e32 v105, 1.0, v105
	v_add_f32_e32 v109, 1.0, v109
	v_sqrt_f32_e32 v154, v154
	v_fmac_f32_e32 v96, v156, v97
	v_mul_f32_e32 v153, v105, v109
	v_mul_f32_e32 v98, v98, v145
	v_mul_f32_e32 v96, v102, v96
	v_add_f32_e32 v106, 1.0, v106
	v_add_f32_e32 v110, 1.0, v110
	v_rcp_f32_e32 v153, v153
	v_mul_f32_e32 v97, v100, v101
	v_fmac_f32_e32 v96, v155, v98
	v_mul_f32_e32 v152, v106, v110
	v_mul_f32_e32 v99, v99, v146
	v_mul_f32_e32 v97, v102, v97
	v_mul_f32_e32 v96, v103, v96
	v_add_f32_e32 v107, 1.0, v107
	v_add_f32_e32 v111, 1.0, v111
	v_rcp_f32_e32 v152, v152
	v_fmac_f32_e32 v96, v154, v99
	v_mul_f32_e32 v97, v103, v97
	v_mul_f32_e32 v151, v107, v111
	ds_bpermute_b32 v98, v128, v97
	ds_bpermute_b32 v99, v128, v96
	v_rcp_f32_e32 v151, v151
	v_mul_f32_e32 v109, v109, v153
	v_mul_f32_e32 v109, v109, v133
	v_mul_f32_e32 v110, v110, v152
	v_mul_f32_e32 v110, v110, v133
	v_exp_f32_e32 v109, v109
	v_mul_f32_e32 v111, v111, v151
	s_waitcnt lgkmcnt(0)
	v_fma_f32 v99, v97, v99, v96
	v_mul_f32_e32 v98, v97, v98
	v_mul_f32_e32 v111, v111, v133
	v_exp_f32_e32 v110, v110
	v_cndmask_b32_e64 v96, v99, v96, s[44:45]
	v_cndmask_b32_e64 v97, v98, v97, s[44:45]
	ds_bpermute_b32 v98, v126, v97
	ds_bpermute_b32 v99, v126, v96
	v_exp_f32_e32 v111, v111
	v_mul_f32_e32 v105, v105, v153
	v_fma_f32 v153, -v109, v109, 1.0 clamp
	v_mul_f32_e32 v106, v106, v152
	v_fma_f32 v152, -v110, v110, 1.0 clamp
	v_sqrt_f32_e32 v153, v153
	v_mul_f32_e32 v107, v107, v151
	v_fma_f32 v151, -v111, v111, 1.0 clamp
	v_sqrt_f32_e32 v152, v152
	s_waitcnt lgkmcnt(0)
	v_fma_f32 v99, v97, v99, v96
	v_mul_f32_e32 v98, v97, v98
	v_fmac_f32_e32 v104, 0, v108
	v_mul_f32_e32 v105, v105, v149
	v_cndmask_b32_e64 v99, v96, v99, s[46:47]
	v_cndmask_b32_e64 v96, v97, v98, s[46:47]
	v_mul_f32_e32 v97, v109, v104
	v_sqrt_f32_e32 v151, v151
	v_fmac_f32_e32 v97, v153, v105
	v_mul_f32_e32 v106, v106, v150
	v_mul_f32_e32 v97, v110, v97
	ds_bpermute_b32 v98, v129, v99
	v_mul_f32_e32 v99, v108, v109
	v_fmac_f32_e32 v97, v152, v106
	v_mul_f32_e32 v107, v107, v147
	v_mul_f32_e32 v99, v110, v99
	v_mul_f32_e32 v97, v111, v97
	v_fmac_f32_e32 v97, v151, v107
	v_mul_f32_e32 v99, v111, v99
	ds_bpermute_b32 v100, v128, v99
	ds_bpermute_b32 v101, v128, v97
	v_mfma_f32_16x16x32_bf16 v[80:83], v[0:3], v[32:35], 0
	ds_bpermute_b32 v96, v129, v96
	s_waitcnt lgkmcnt(2)
	v_mul_f32_e32 v100, v99, v100
	s_waitcnt lgkmcnt(1)
	v_fma_f32 v101, v99, v101, v97
	v_cndmask_b32_e64 v97, v101, v97, s[44:45]
	v_cndmask_b32_e64 v99, v100, v99, s[44:45]
	v_mfma_f32_16x16x32_bf16 v[88:91], v[8:11], v[32:35], 0
	ds_bpermute_b32 v100, v126, v99
	ds_bpermute_b32 v101, v126, v97
	s_waitcnt lgkmcnt(1)
	v_mul_f32_e32 v100, v99, v100
	v_mfma_f32_16x16x32_bf16 v[84:87], v[4:7], v[36:39], v[80:83]
	s_waitcnt lgkmcnt(0)
	v_fma_f32 v101, v99, v101, v97
	v_cndmask_b32_e64 v97, v97, v101, s[46:47]
	v_cndmask_b32_e64 v99, v99, v100, s[46:47]
	v_mfma_f32_16x16x32_bf16 v[92:95], v[12:15], v[36:39], v[88:91]
	ds_bpermute_b32 v99, v129, v99
	ds_bpermute_b32 v97, v129, v97
	v_mfma_f32_16x16x32_bf16 v[80:83], v[0:3], v[40:43], 0
	v_mfma_f32_16x16x32_bf16 v[88:91], v[8:11], v[40:43], 0
	v_mfma_f32_16x16x32_bf16 v[80:83], v[4:7], v[44:47], v[80:83]
	v_mfma_f32_16x16x32_bf16 v[88:91], v[12:15], v[44:47], v[88:91]
	s_and_saveexec_b64 s[4:5], s[44:45]
	s_cbranch_execz .LBB0_717
	s_waitcnt lgkmcnt(0)
	v_fmac_f32_e32 v97, v98, v99
	v_mul_f32_e32 v96, v96, v99
	global_store_dwordx2 v[116:117], v[96:97], off offset:-4
.LBB0_717:
	s_or_b64 exec, exec, s[4:5]
	v_mul_f32_e32 v134, 0xbfb8aa3b, v134
	s_nop 2
	v_mul_f32_e32 v135, 0xbfb8aa3b, v135
	v_fmamk_f32 v87, v87, 0xbfb8aa3b, v134
	v_fmamk_f32 v83, v83, 0xbfb8aa3b, v135
	v_exp_f32_e32 v87, v87
	v_exp_f32_e32 v83, v83
	v_add_f32_e32 v87, 1.0, v87
	v_add_f32_e32 v83, 1.0, v83
	s_waitcnt lgkmcnt(1)
	v_mul_f32_e32 v99, v87, v83
	v_rcp_f32_e32 v99, v99
	v_fmamk_f32 v86, v86, 0xbfb8aa3b, v134
	v_fmamk_f32 v82, v82, 0xbfb8aa3b, v135
	v_exp_f32_e32 v86, v86
	v_mul_f32_e32 v83, v83, v99
	v_mul_f32_e32 v136, 0xbfb8aa3b, v136
	v_mul_f32_e32 v83, v83, v136
	v_exp_f32_e32 v83, v83
	v_mul_f32_e32 v87, v87, v99
	v_exp_f32_e32 v82, v82
	v_mul_f32_e32 v87, v87, v146
	v_fma_f32 v99, -v83, v83, 1.0 clamp
	v_sqrt_f32_e32 v99, v99
	v_add_f32_e32 v86, 1.0, v86
	v_add_f32_e32 v82, 1.0, v82
	v_mul_f32_e32 v87, v87, v99
	v_mul_f32_e32 v99, v86, v82
	v_rcp_f32_e32 v99, v99
	v_fmamk_f32 v95, v95, 0xbfb8aa3b, v134
	v_mul_f32_e32 v82, v82, v99
	v_mul_f32_e32 v82, v82, v136
	v_mul_f32_e32 v86, v86, v99
	v_exp_f32_e32 v99, v82
	v_fmamk_f32 v91, v91, 0xbfb8aa3b, v135
	v_fmamk_f32 v81, v81, 0xbfb8aa3b, v135
	v_exp_f32_e32 v95, v95
	v_fma_f32 v82, -v99, v99, 1.0 clamp
	v_sqrt_f32_e32 v100, v82
	v_fmamk_f32 v82, v85, 0xbfb8aa3b, v134
	v_exp_f32_e32 v91, v91
	v_exp_f32_e32 v82, v82
	v_exp_f32_e32 v81, v81
	v_add_f32_e32 v95, 1.0, v95
	v_add_f32_e32 v91, 1.0, v91
	v_add_f32_e32 v82, 1.0, v82
	v_add_f32_e32 v81, 1.0, v81
	v_mul_f32_e32 v96, v95, v91
	v_mul_f32_e32 v85, v82, v81
	v_rcp_f32_e32 v96, v96
	v_rcp_f32_e32 v85, v85
	v_mul_f32_e32 v91, v91, v96
	v_mul_f32_e32 v81, v81, v85
	v_mul_f32_e32 v91, v91, v136
	v_mul_f32_e32 v81, v81, v136
	v_exp_f32_e32 v91, v91
	v_exp_f32_e32 v81, v81
	v_mul_f32_e32 v82, v82, v85
	v_mul_f32_e32 v95, v95, v96
	v_fma_f32 v96, -v91, v91, 1.0 clamp
	v_fmamk_f32 v94, v94, 0xbfb8aa3b, v134
	v_fmamk_f32 v90, v90, 0xbfb8aa3b, v135
	v_mul_f32_e32 v101, v82, v144
	v_fma_f32 v82, -v81, v81, 1.0 clamp
	v_exp_f32_e32 v94, v94
	v_exp_f32_e32 v90, v90
	v_sqrt_f32_e32 v96, v96
	v_fmamk_f32 v93, v93, 0xbfb8aa3b, v134
	v_fmamk_f32 v89, v89, 0xbfb8aa3b, v135
	v_sqrt_f32_e32 v85, v82
	v_exp_f32_e32 v93, v93
	v_exp_f32_e32 v89, v89
	v_fmamk_f32 v82, v84, 0xbfb8aa3b, v134
	v_fmamk_f32 v80, v80, 0xbfb8aa3b, v135
	v_fmamk_f32 v92, v92, 0xbfb8aa3b, v134
	v_fmamk_f32 v88, v88, 0xbfb8aa3b, v135
	v_exp_f32_e32 v82, v82
	v_exp_f32_e32 v80, v80
	v_mul_f32_e32 v95, v95, v147
	v_add_f32_e32 v94, 1.0, v94
	v_add_f32_e32 v90, 1.0, v90
	v_exp_f32_e32 v92, v92
	v_exp_f32_e32 v88, v88
	v_mul_f32_e32 v95, v96, v95
	v_mul_f32_e32 v96, v94, v90
	v_rcp_f32_e32 v96, v96
	v_add_f32_e32 v93, 1.0, v93
	v_add_f32_e32 v89, 1.0, v89
	s_waitcnt lgkmcnt(0)
	v_mul_f32_e32 v97, v93, v89
	v_add_f32_e32 v82, 1.0, v82
	v_add_f32_e32 v80, 1.0, v80
	v_rcp_f32_e32 v97, v97
	v_add_f32_e32 v92, 1.0, v92
	v_add_f32_e32 v88, 1.0, v88
	v_mul_f32_e32 v84, v82, v80
	v_mul_f32_e32 v98, v92, v88
	v_rcp_f32_e32 v84, v84
	v_mul_f32_e32 v90, v90, v96
	v_rcp_f32_e32 v98, v98
	v_mul_f32_e32 v90, v90, v136
	v_mul_f32_e32 v89, v89, v97
	v_exp_f32_e32 v90, v90
	v_mul_f32_e32 v89, v89, v136
	v_mul_f32_e32 v80, v80, v84
	v_mul_f32_e32 v88, v88, v98
	v_mul_f32_e32 v80, v80, v136
	v_exp_f32_e32 v89, v89
	v_mul_f32_e32 v88, v88, v136
	v_mul_f32_e32 v82, v82, v84
	v_exp_f32_e32 v84, v80
	v_mul_f32_e32 v94, v94, v96
	v_fma_f32 v96, -v90, v90, 1.0 clamp
	v_exp_f32_e32 v88, v88
	v_sqrt_f32_e32 v96, v96
	v_mul_f32_e32 v93, v93, v97
	v_fma_f32 v97, -v89, v89, 1.0 clamp
	v_fma_f32 v80, -v84, v84, 1.0 clamp
	v_sqrt_f32_e32 v97, v97
	v_mul_f32_e32 v92, v92, v98
	v_fma_f32 v98, -v88, v88, 1.0 clamp
	v_fmac_f32_e32 v95, 0, v91
	v_fmac_f32_e32 v87, 0, v83
	v_mul_f32_e32 v94, v94, v150
	v_mul_f32_e32 v86, v86, v145
	v_sqrt_f32_e32 v103, v80
	v_mul_f32_e32 v80, v90, v95
	v_mul_f32_e32 v87, v99, v87
	v_sqrt_f32_e32 v98, v98
	v_fmac_f32_e32 v80, v96, v94
	v_fmac_f32_e32 v87, v86, v100
	v_mul_f32_e32 v93, v93, v149
	v_mul_f32_e32 v80, v89, v80
	v_mul_f32_e32 v86, v81, v87
	v_mul_f32_e32 v102, v82, v143
	v_mul_f32_e32 v82, v91, v90
	v_fmac_f32_e32 v80, v97, v93
	v_mul_f32_e32 v83, v83, v99
	v_fmac_f32_e32 v86, v101, v85
	v_mul_f32_e32 v92, v92, v148
	v_mul_f32_e32 v82, v89, v82
	v_mul_f32_e32 v80, v88, v80
	v_mul_f32_e32 v81, v81, v83
	v_mul_f32_e32 v83, v84, v86
	v_fmac_f32_e32 v80, v98, v92
	v_mul_f32_e32 v82, v88, v82
	v_fmac_f32_e32 v83, v102, v103
	v_mul_f32_e32 v81, v84, v81
	ds_bpermute_b32 v88, v125, v82
	ds_bpermute_b32 v89, v125, v80
	ds_bpermute_b32 v84, v125, v81
	ds_bpermute_b32 v85, v125, v83
	s_waitcnt lgkmcnt(3)
	v_mul_f32_e32 v88, v82, v88
	s_waitcnt lgkmcnt(2)
	v_fma_f32 v89, v82, v89, v80
	s_waitcnt lgkmcnt(1)
	v_mul_f32_e32 v84, v81, v84
	s_waitcnt lgkmcnt(0)
	v_fma_f32 v85, v81, v85, v83
	v_cndmask_b32_e64 v80, v89, v80, s[40:41]
	v_cndmask_b32_e64 v82, v88, v82, s[40:41]
	v_cndmask_b32_e64 v83, v85, v83, s[40:41]
	v_cndmask_b32_e64 v81, v84, v81, s[40:41]
	ds_bpermute_b32 v88, v126, v82
	ds_bpermute_b32 v89, v126, v80
	ds_bpermute_b32 v84, v126, v81
	ds_bpermute_b32 v85, v126, v83
	s_waitcnt lgkmcnt(3)
	v_mul_f32_e32 v88, v82, v88
	s_waitcnt lgkmcnt(2)
	v_fma_f32 v89, v82, v89, v80
	s_waitcnt lgkmcnt(1)
	v_mul_f32_e32 v84, v81, v84
	s_waitcnt lgkmcnt(0)
	v_fma_f32 v85, v81, v85, v83
	v_cndmask_b32_e64 v89, v80, v89, s[42:43]
	v_cndmask_b32_e64 v80, v82, v88, s[42:43]
	v_cndmask_b32_e64 v85, v83, v85, s[42:43]
	v_cndmask_b32_e64 v81, v81, v84, s[42:43]
	ds_bpermute_b32 v80, v127, v80
	ds_bpermute_b32 v82, v127, v89
	ds_bpermute_b32 v83, v127, v81
	ds_bpermute_b32 v81, v127, v85
	s_and_saveexec_b64 s[4:5], s[44:45]
	s_cbranch_execz .LBB0_719
	v_lshl_add_u64 v[84:85], v[118:119], 3, s[60:61]
	s_waitcnt lgkmcnt(0)
	v_fmac_f32_e32 v81, v82, v83
	v_mul_f32_e32 v80, v80, v83
	global_store_dwordx2 v[84:85], v[80:81], off

.LBB0_821:
	s_waitcnt vmcnt(13)
	v_mfma_f32_16x16x32_bf16 v[102:105], v[0:3], v[64:67], 0
	v_add_u32_e32 v82, s26, v126
	v_add_u32_e32 v32, 16, v82
	v_add_u32_e32 v34, 0x210, v82
	v_mfma_f32_16x16x32_bf16 v[106:109], v[8:11], v[64:67], 0
	v_ashrrev_i32_e32 v33, 31, v32
	v_ashrrev_i32_e32 v35, 31, v34
	v_add_u32_e32 v84, 0x410, v82
	s_waitcnt vmcnt(12)
	v_mfma_f32_16x16x32_bf16 v[64:67], v[4:7], v[72:75], v[102:105]
	v_add_u32_e32 v90, 0x610, v82
	v_lshlrev_b64 v[16:17], 7, v[32:33]
	v_lshlrev_b64 v[24:25], 7, v[34:35]
	s_waitcnt vmcnt(11)
	v_mfma_f32_16x16x32_bf16 v[102:105], v[0:3], v[68:71], 0
	v_lshlrev_b64 v[32:33], 2, v[32:33]
	v_ashrrev_i32_e32 v85, 31, v84
	v_ashrrev_i32_e32 v91, 31, v90
	v_lshl_add_u64 v[20:21], v[116:117], 0, v[16:17]
	v_lshl_add_u64 v[28:29], v[116:117], 0, v[24:25]
	v_lshl_add_u64 v[36:37], s[38:39], 0, v[32:33]
	v_lshl_add_u64 v[34:35], v[34:35], 2, s[38:39]
	v_lshl_add_u64 v[80:81], s[0:1], 0, v[32:33]
	v_lshlrev_b64 v[32:33], 7, v[84:85]
	v_lshlrev_b64 v[40:41], 7, v[90:91]
	v_mfma_f32_16x16x32_bf16 v[72:75], v[12:15], v[72:75], v[106:109]
	global_load_dwordx4 v[16:19], v[20:21], off
	s_nop 0
	global_load_dwordx4 v[20:23], v[20:21], off offset:64
	s_nop 0
	global_load_dwordx4 v[24:27], v[28:29], off
	s_nop 0
	global_load_dwordx4 v[28:31], v[28:29], off offset:64
	v_lshl_add_u64 v[44:45], v[116:117], 0, v[40:41]
	v_mfma_f32_16x16x32_bf16 v[106:109], v[8:11], v[68:71], 0
	global_load_dword v134, v[36:37], off
	global_load_dword v135, v[34:35], off
	v_lshl_add_u64 v[36:37], v[116:117], 0, v[32:33]
	s_waitcnt vmcnt(16)
	v_mfma_f32_16x16x32_bf16 v[68:71], v[4:7], v[76:79], v[102:105]
	v_lshl_add_u64 v[84:85], v[84:85], 2, s[38:39]
	global_load_dword v136, v[80:81], off
	global_load_dwordx4 v[32:35], v[36:37], off
	s_nop 0
	global_load_dwordx4 v[36:39], v[36:37], off offset:64
	s_waitcnt vmcnt(10)
	v_mfma_f32_16x16x32_bf16 v[102:105], v[0:3], v[48:51], 0
	global_load_dwordx4 v[40:43], v[44:45], off
	s_nop 0
	global_load_dwordx4 v[44:47], v[44:45], off offset:64
	v_add_u32_e32 v140, s35, v133
	global_load_dword v137, v[84:85], off
	v_lshl_add_u64 v[84:85], v[90:91], 2, s[38:39]
	global_load_dword v138, v[84:85], off
	global_load_dword v139, v[80:81], off offset:2048
	v_lshl_add_u64 v[80:81], v[172:173], 0, s[70:71]
	ds_read_u16 v90, v140
	ds_read_u16 v91, v140 offset:1024
	ds_read_u16 v93, v140 offset:2048
	ds_read_u16 v97, v140 offset:3072
	ds_read_u16 v98, v140 offset:4096
	ds_read_u16 v99, v140 offset:5120
	ds_read_u16 v100, v140 offset:6144
	ds_bpermute_b32 v83, v80, v122
	ds_bpermute_b32 v92, v80, v114
	v_mfma_f32_16x16x32_bf16 v[76:79], v[12:15], v[76:79], v[106:109]
	ds_bpermute_b32 v84, v80, v123
	ds_bpermute_b32 v85, v80, v124
	ds_bpermute_b32 v101, v80, v125
	v_mfma_f32_16x16x32_bf16 v[106:109], v[8:11], v[48:51], 0
	v_mul_f32_e32 v96, 0xbfb8aa3b, v96
	s_nop 2
	v_mul_f32_e32 v95, 0xbfb8aa3b, v95
	v_fmamk_f32 v75, v75, 0xbfb8aa3b, v96
	v_mfma_f32_16x16x32_bf16 v[48:51], v[4:7], v[56:59], v[102:105]
	v_fmamk_f32 v79, v79, 0xbfb8aa3b, v95
	v_exp_f32_e32 v75, v75
	v_exp_f32_e32 v79, v79
	v_mfma_f32_16x16x32_bf16 v[102:105], v[0:3], v[52:55], 0
	v_add_f32_e32 v75, 1.0, v75
	v_add_f32_e32 v79, 1.0, v79
	v_mfma_f32_16x16x32_bf16 v[56:59], v[12:15], v[56:59], v[106:109]
	v_fmamk_f32 v74, v74, 0xbfb8aa3b, v96
	v_fmamk_f32 v78, v78, 0xbfb8aa3b, v95
	v_mfma_f32_16x16x32_bf16 v[106:109], v[8:11], v[52:55], 0
	v_exp_f32_e32 v74, v74
	v_exp_f32_e32 v78, v78
	v_mfma_f32_16x16x32_bf16 v[52:55], v[4:7], v[60:63], v[102:105]
	v_add_f32_e32 v74, 1.0, v74
	v_add_f32_e32 v78, 1.0, v78
	ds_read_u16 v102, v140 offset:19456
	s_waitcnt lgkmcnt(12)
	v_lshlrev_b32_e32 v90, 16, v90
	s_waitcnt lgkmcnt(11)
	v_lshlrev_b32_e32 v91, 16, v91
	s_waitcnt lgkmcnt(4)
	v_fma_f32 v90, v83, v90, v92
	v_lshlrev_b32_e32 v93, 16, v93
	s_waitcnt lgkmcnt(3)
	v_fmac_f32_e32 v90, v84, v91
	v_fma_f32 v91, v83, v91, v92
	v_lshlrev_b32_e32 v97, 16, v97
	s_waitcnt lgkmcnt(2)
	v_fmac_f32_e32 v90, v85, v93
	v_fmac_f32_e32 v91, v84, v93
	v_fma_f32 v93, v83, v93, v92
	v_lshlrev_b32_e32 v98, 16, v98
	s_waitcnt lgkmcnt(1)
	v_fmac_f32_e32 v90, v101, v97
	v_fmac_f32_e32 v91, v85, v97
	v_fmac_f32_e32 v93, v84, v97
	v_fma_f32 v97, v83, v97, v92
	v_lshlrev_b32_e32 v99, 16, v99
	v_fmac_f32_e32 v91, v101, v98
	v_fmac_f32_e32 v93, v85, v98
	v_fmac_f32_e32 v97, v84, v98
	ds_read_u16 v98, v140 offset:16384
	ds_read_u16 v103, v140 offset:20480
	ds_read_u16 v104, v140 offset:21504
	ds_read_u16 v105, v140 offset:22528
	v_lshlrev_b32_e32 v100, 16, v100
	v_fmac_f32_e32 v93, v101, v99
	v_fmac_f32_e32 v97, v85, v99
	ds_read_u16 v99, v140 offset:17408
	v_fmac_f32_e32 v97, v101, v100
	ds_read_u16 v100, v140 offset:18432
	s_waitcnt lgkmcnt(5)
	v_lshlrev_b32_e32 v98, 16, v98
	v_fma_f32 v98, v83, v98, v92
	s_waitcnt lgkmcnt(1)
	v_lshlrev_b32_e32 v99, 16, v99
	v_lshlrev_b32_e32 v102, 16, v102
	s_waitcnt lgkmcnt(0)
	v_lshlrev_b32_e32 v100, 16, v100
	v_fmac_f32_e32 v98, v84, v99
	v_fma_f32 v99, v83, v99, v92
	v_lshlrev_b32_e32 v103, 16, v103
	v_fmac_f32_e32 v98, v85, v100
	v_fmac_f32_e32 v99, v84, v100
	v_fma_f32 v100, v83, v100, v92
	v_fmac_f32_e32 v92, v83, v102
	v_lshlrev_b32_e32 v104, 16, v104
	v_fmac_f32_e32 v100, v84, v102
	v_fmac_f32_e32 v92, v84, v103
	v_ashrrev_i32_e32 v83, 31, v82
	v_fmac_f32_e32 v99, v85, v102
	v_fmac_f32_e32 v100, v85, v103
	v_fmac_f32_e32 v92, v85, v104
	v_lshl_add_u64 v[84:85], v[82:83], 2, s[48:49]
	v_mul_f32_e32 v83, v75, v79
	v_rcp_f32_e32 v83, v83
	v_lshlrev_b32_e32 v105, 16, v105
	v_fmac_f32_e32 v92, v101, v105
	v_fmamk_f32 v73, v73, 0xbfb8aa3b, v96
	v_mul_f32_e32 v79, v79, v83
	v_mul_f32_e32 v94, 0xbfb8aa3b, v94
	v_mul_f32_e32 v79, v79, v94
	v_exp_f32_e32 v79, v79
	v_mul_f32_e32 v75, v75, v83
	v_mul_f32_e32 v75, v75, v92
	v_fmamk_f32 v77, v77, 0xbfb8aa3b, v95
	v_fma_f32 v83, -v79, v79, 1.0 clamp
	v_sqrt_f32_e32 v83, v83
	v_exp_f32_e32 v73, v73
	v_exp_f32_e32 v77, v77
	v_fmac_f32_e32 v100, v101, v104
	v_mul_f32_e32 v75, v83, v75
	v_mul_f32_e32 v83, v74, v78
	v_rcp_f32_e32 v83, v83
	v_add_f32_e32 v73, 1.0, v73
	v_add_f32_e32 v77, 1.0, v77
	v_mul_f32_e32 v78, v78, v83
	v_mul_f32_e32 v78, v78, v94
	v_exp_f32_e32 v78, v78
	v_mul_f32_e32 v74, v74, v83
	v_mul_f32_e32 v74, v74, v100
	v_fma_f32 v83, -v78, v78, 1.0 clamp
	v_sqrt_f32_e32 v83, v83
	v_fmamk_f32 v72, v72, 0xbfb8aa3b, v96
	v_fmamk_f32 v76, v76, 0xbfb8aa3b, v95
	v_exp_f32_e32 v72, v72
	v_mul_f32_e32 v74, v83, v74
	v_mul_f32_e32 v83, v73, v77
	v_rcp_f32_e32 v83, v83
	v_exp_f32_e32 v76, v76
	v_fmac_f32_e32 v99, v101, v103
	v_add_f32_e32 v72, 1.0, v72
	v_mul_f32_e32 v77, v77, v83
	v_mul_f32_e32 v77, v77, v94
	v_mul_f32_e32 v73, v73, v83
	v_exp_f32_e32 v83, v77
	v_mul_f32_e32 v73, v73, v99
	v_add_f32_e32 v76, 1.0, v76
	v_fmac_f32_e32 v98, v101, v102
	v_fma_f32 v77, -v83, v83, 1.0 clamp
	v_sqrt_f32_e32 v77, v77
	v_fmamk_f32 v67, v67, 0xbfb8aa3b, v96
	v_mul_f32_e32 v73, v77, v73
	v_mul_f32_e32 v77, v72, v76
	v_rcp_f32_e32 v77, v77
	v_fmamk_f32 v71, v71, 0xbfb8aa3b, v95
	v_exp_f32_e32 v67, v67
	v_exp_f32_e32 v71, v71
	v_mul_f32_e32 v76, v76, v77
	v_mul_f32_e32 v76, v76, v94
	v_exp_f32_e32 v101, v76
	v_mul_f32_e32 v72, v72, v77
	v_mul_f32_e32 v72, v72, v98
	v_add_f32_e32 v67, 1.0, v67
	v_fma_f32 v76, -v101, v101, 1.0 clamp
	v_sqrt_f32_e32 v76, v76
	v_add_f32_e32 v71, 1.0, v71
	v_mul_f32_e32 v72, v76, v72
	v_mul_f32_e32 v76, v67, v71
	v_rcp_f32_e32 v76, v76
	v_fmamk_f32 v66, v66, 0xbfb8aa3b, v96
	v_fmamk_f32 v70, v70, 0xbfb8aa3b, v95
	v_exp_f32_e32 v66, v66
	v_mul_f32_e32 v67, v67, v76
	v_mul_f32_e32 v77, v67, v97
	v_mul_f32_e32 v67, v71, v76
	v_mul_f32_e32 v67, v67, v94
	v_exp_f32_e32 v70, v70
	v_exp_f32_e32 v67, v67
	v_add_f32_e32 v66, 1.0, v66
	v_add_f32_e32 v70, 1.0, v70
	v_fma_f32 v71, -v67, v67, 1.0 clamp
	v_mul_f32_e32 v76, v66, v70
	v_fmamk_f32 v65, v65, 0xbfb8aa3b, v96
	v_fmamk_f32 v69, v69, 0xbfb8aa3b, v95
	v_rcp_f32_e32 v76, v76
	v_exp_f32_e32 v65, v65
	v_exp_f32_e32 v69, v69
	v_sqrt_f32_e32 v71, v71
	v_mul_f32_e32 v66, v66, v76
	v_add_f32_e32 v65, 1.0, v65
	v_add_f32_e32 v69, 1.0, v69
	v_mul_f32_e32 v71, v71, v77
	v_mul_f32_e32 v77, v66, v93
	v_mul_f32_e32 v66, v70, v76
	v_mul_f32_e32 v76, v65, v69
	v_rcp_f32_e32 v76, v76
	v_mul_f32_e32 v66, v66, v94
	v_mul_f32_e32 v69, v69, v76
	v_mul_f32_e32 v69, v69, v94
	v_exp_f32_e32 v69, v69
	v_mul_f32_e32 v65, v65, v76
	v_fmamk_f32 v64, v64, 0xbfb8aa3b, v96
	v_fmamk_f32 v68, v68, 0xbfb8aa3b, v95
	v_fma_f32 v76, -v69, v69, 1.0 clamp
	v_exp_f32_e32 v64, v64
	v_exp_f32_e32 v68, v68
	v_exp_f32_e32 v66, v66
	v_sqrt_f32_e32 v76, v76
	v_mul_f32_e32 v65, v65, v91
	v_add_f32_e32 v64, 1.0, v64
	v_add_f32_e32 v68, 1.0, v68
	v_fma_f32 v70, -v66, v66, 1.0 clamp
	v_mul_f32_e32 v65, v76, v65
	v_mul_f32_e32 v76, v64, v68
	v_rcp_f32_e32 v76, v76
	v_sqrt_f32_e32 v70, v70
	ds_bpermute_b32 v81, v80, v113
	ds_bpermute_b32 v86, v80, v115
	v_mul_f32_e32 v64, v64, v76
	v_mul_f32_e32 v70, v70, v77
	v_mul_f32_e32 v77, v64, v90
	v_mul_f32_e32 v64, v68, v76
	v_mul_f32_e32 v64, v64, v94
	v_exp_f32_e32 v64, v64
	v_mfma_f32_16x16x32_bf16 v[60:63], v[12:15], v[60:63], v[106:109]
	v_fma_f32 v68, -v64, v64, 1.0 clamp
	v_sqrt_f32_e32 v68, v68
	s_nop 0
	v_mul_f32_e32 v68, v68, v77
	v_fma_f32 v76, 0, v64, v68
	v_fma_f32 v76, v69, v76, v65
	v_mul_f32_e32 v77, v64, v69
	v_fma_f32 v76, v66, v76, v70
	v_mul_f32_e32 v77, v66, v77
	v_fma_f32 v76, v67, v76, v71
	v_mul_f32_e32 v77, v67, v77
	ds_bpermute_b32 v94, v131, v77
	ds_bpermute_b32 v95, v131, v76
	s_waitcnt lgkmcnt(1)
	v_mul_f32_e32 v94, v77, v94
	s_waitcnt lgkmcnt(0)
	v_fma_f32 v95, v77, v95, v76
	v_cndmask_b32_e64 v76, v95, v76, s[44:45]
	v_cndmask_b32_e64 v77, v94, v77, s[44:45]
	ds_bpermute_b32 v94, v129, v77
	ds_bpermute_b32 v95, v129, v76
	s_waitcnt lgkmcnt(1)
	v_mul_f32_e32 v94, v77, v94
	s_waitcnt lgkmcnt(0)
	v_fma_f32 v95, v77, v95, v76
	v_cndmask_b32_e64 v95, v76, v95, s[46:47]
	v_cndmask_b32_e64 v76, v77, v94, s[46:47]
	ds_bpermute_b32 v94, v132, v76
	ds_bpermute_b32 v96, v132, v95
	ds_bpermute_b32 v77, v131, v95
	v_mul_f32_e32 v95, v101, v83
	v_mul_f32_e32 v95, v78, v95
	v_mul_f32_e32 v95, v79, v95
	s_waitcnt lgkmcnt(1)
	v_fmac_f32_e32 v96, v81, v94
	v_fma_f32 v94, 0, v101, v72
	v_fma_f32 v94, v83, v94, v73
	v_fma_f32 v94, v78, v94, v74
	v_fma_f32 v94, v79, v94, v75
	ds_bpermute_b32 v102, v131, v95
	ds_bpermute_b32 v103, v131, v94
	ds_bpermute_b32 v76, v131, v76
	s_waitcnt lgkmcnt(2)
	v_mul_f32_e32 v102, v95, v102
	s_waitcnt lgkmcnt(1)
	v_fma_f32 v103, v95, v103, v94
	v_cndmask_b32_e64 v94, v103, v94, s[44:45]
	v_cndmask_b32_e64 v95, v102, v95, s[44:45]
	ds_bpermute_b32 v102, v129, v95
	ds_bpermute_b32 v103, v129, v94
	s_waitcnt lgkmcnt(1)
	v_mul_f32_e32 v102, v95, v102
	s_waitcnt lgkmcnt(0)
	v_fma_f32 v103, v95, v103, v94
	v_cndmask_b32_e64 v94, v94, v103, s[46:47]
	v_cndmask_b32_e64 v95, v95, v102, s[46:47]
	ds_bpermute_b32 v95, v131, v95
	ds_bpermute_b32 v94, v131, v94
	s_waitcnt lgkmcnt(1)
	v_cndmask_b32_e64 v95, v95, 1.0, s[44:45]
	s_waitcnt lgkmcnt(0)
	v_cndmask_b32_e64 v94, v94, 0, s[44:45]
	v_fmac_f32_e32 v94, v96, v95
	v_fmac_f32_e32 v72, v101, v94
	v_fmac_f32_e32 v73, v83, v72
	v_fmac_f32_e32 v74, v78, v73
	v_fmac_f32_e32 v75, v79, v74
	s_and_saveexec_b64 s[4:5], s[68:69]
	s_cbranch_execz .LBB0_823
	global_store_dword v[84:85], v75, off
.LBB0_823:
	s_or_b64 exec, exec, s[4:5]
	v_mul_f32_e32 v89, 0xbfb8aa3b, v89
	v_mul_f32_e32 v88, 0xbfb8aa3b, v88
	v_fmamk_f32 v59, v59, 0xbfb8aa3b, v89
	v_fmamk_f32 v63, v63, 0xbfb8aa3b, v88
	v_exp_f32_e32 v59, v59
	v_exp_f32_e32 v63, v63
	v_add_f32_e32 v59, 1.0, v59
	v_add_f32_e32 v63, 1.0, v63
	v_mul_f32_e32 v78, v59, v63
	v_rcp_f32_e32 v78, v78
	v_fmamk_f32 v58, v58, 0xbfb8aa3b, v89
	v_fmamk_f32 v62, v62, 0xbfb8aa3b, v88
	v_exp_f32_e32 v58, v58
	v_mul_f32_e32 v63, v63, v78
	s_waitcnt vmcnt(14)
	v_mul_f32_e32 v87, 0xbfb8aa3b, v87
	v_mul_f32_e32 v63, v63, v87
	v_exp_f32_e32 v63, v63
	v_mul_f32_e32 v59, v59, v78
	v_exp_f32_e32 v62, v62
	v_mul_f32_e32 v59, v59, v92
	v_fma_f32 v78, -v63, v63, 1.0 clamp
	v_sqrt_f32_e32 v78, v78
	v_add_f32_e32 v58, 1.0, v58
	v_add_f32_e32 v62, 1.0, v62
	v_mul_f32_e32 v59, v78, v59
	v_mul_f32_e32 v78, v58, v62
	v_rcp_f32_e32 v78, v78
	v_fmamk_f32 v57, v57, 0xbfb8aa3b, v89
	v_fmamk_f32 v61, v61, 0xbfb8aa3b, v88
	v_mul_f32_e32 v62, v62, v78
	v_mul_f32_e32 v62, v62, v87
	v_exp_f32_e32 v62, v62
	v_mul_f32_e32 v58, v58, v78
	v_exp_f32_e32 v57, v57
	v_exp_f32_e32 v61, v61
	v_fma_f32 v78, -v62, v62, 1.0 clamp
	v_sqrt_f32_e32 v78, v78
	v_mul_f32_e32 v58, v58, v100
	v_add_f32_e32 v57, 1.0, v57
	v_add_f32_e32 v61, 1.0, v61
	v_mul_f32_e32 v58, v78, v58
	v_mul_f32_e32 v78, v57, v61
	v_rcp_f32_e32 v78, v78
	v_fmamk_f32 v56, v56, 0xbfb8aa3b, v89
	v_mul_f32_e32 v61, v61, v78
	v_mul_f32_e32 v61, v61, v87
	v_exp_f32_e32 v61, v61
	v_mul_f32_e32 v57, v57, v78
	v_fmamk_f32 v60, v60, 0xbfb8aa3b, v88
	v_exp_f32_e32 v56, v56
	v_fma_f32 v78, -v61, v61, 1.0 clamp
	v_exp_f32_e32 v60, v60
	v_sqrt_f32_e32 v78, v78
	v_mul_f32_e32 v57, v57, v99
	v_add_f32_e32 v56, 1.0, v56
	v_add_f32_e32 v60, 1.0, v60
	v_mul_f32_e32 v57, v78, v57
	v_mul_f32_e32 v78, v56, v60
	v_rcp_f32_e32 v78, v78
	v_fmamk_f32 v51, v51, 0xbfb8aa3b, v89
	v_mul_f32_e32 v60, v60, v78
	v_mul_f32_e32 v60, v60, v87
	v_exp_f32_e32 v60, v60
	v_mul_f32_e32 v56, v56, v78
	v_fmamk_f32 v55, v55, 0xbfb8aa3b, v88
	v_exp_f32_e32 v51, v51
	v_fma_f32 v78, -v60, v60, 1.0 clamp
	v_exp_f32_e32 v55, v55
	v_sqrt_f32_e32 v78, v78
	v_mul_f32_e32 v56, v56, v98
	v_add_f32_e32 v51, 1.0, v51
	v_add_f32_e32 v55, 1.0, v55
	v_mul_f32_e32 v56, v78, v56
	v_mul_f32_e32 v78, v51, v55
	v_rcp_f32_e32 v78, v78
	v_fmamk_f32 v50, v50, 0xbfb8aa3b, v89
	v_mul_f32_e32 v55, v55, v78
	v_mul_f32_e32 v55, v55, v87
	v_exp_f32_e32 v55, v55
	v_mul_f32_e32 v51, v51, v78
	v_fmamk_f32 v54, v54, 0xbfb8aa3b, v88
	v_exp_f32_e32 v50, v50
	v_fma_f32 v78, -v55, v55, 1.0 clamp
	v_exp_f32_e32 v54, v54
	v_sqrt_f32_e32 v78, v78
	v_mul_f32_e32 v51, v51, v97
	v_add_f32_e32 v50, 1.0, v50
	v_add_f32_e32 v54, 1.0, v54
	v_mul_f32_e32 v51, v51, v78
	v_mul_f32_e32 v78, v50, v54
	v_rcp_f32_e32 v78, v78
	v_fmamk_f32 v49, v49, 0xbfb8aa3b, v89
	v_mul_f32_e32 v54, v54, v78
	v_mul_f32_e32 v54, v54, v87
	v_exp_f32_e32 v54, v54
	v_mul_f32_e32 v50, v50, v78
	v_fmamk_f32 v53, v53, 0xbfb8aa3b, v88
	v_exp_f32_e32 v49, v49
	v_fma_f32 v78, -v54, v54, 1.0 clamp
	v_exp_f32_e32 v53, v53
	v_sqrt_f32_e32 v78, v78
	v_mul_f32_e32 v50, v50, v93
	v_add_f32_e32 v49, 1.0, v49
	v_add_f32_e32 v53, 1.0, v53
	v_mul_f32_e32 v50, v50, v78
	v_mul_f32_e32 v78, v49, v53
	v_rcp_f32_e32 v78, v78
	v_fmamk_f32 v48, v48, 0xbfb8aa3b, v89
	v_mul_f32_e32 v53, v53, v78
	v_mul_f32_e32 v53, v53, v87
	v_mul_f32_e32 v49, v49, v78
	v_exp_f32_e32 v78, v53
	v_fmamk_f32 v52, v52, 0xbfb8aa3b, v88
	v_exp_f32_e32 v48, v48
	v_exp_f32_e32 v52, v52
	v_fma_f32 v53, -v78, v78, 1.0 clamp
	v_sqrt_f32_e32 v53, v53
	v_mul_f32_e32 v49, v49, v91
	v_add_f32_e32 v48, 1.0, v48
	v_add_f32_e32 v52, 1.0, v52
	v_mul_f32_e32 v49, v49, v53
	v_mul_f32_e32 v53, v48, v52
	v_rcp_f32_e32 v53, v53
	s_nop 0
	v_mul_f32_e32 v52, v52, v53
	v_mul_f32_e32 v52, v52, v87
	v_exp_f32_e32 v79, v52
	v_mul_f32_e32 v48, v48, v53
	v_mul_f32_e32 v48, v48, v90
	v_mul_f32_e32 v53, v63, v62
	v_fma_f32 v52, -v79, v79, 1.0 clamp
	v_sqrt_f32_e32 v52, v52
	v_mul_f32_e32 v53, v61, v53
	v_mul_f32_e32 v53, v60, v53
	ds_bpermute_b32 v83, v128, v53
	v_mul_f32_e32 v48, v48, v52
	v_fma_f32 v52, 0, v63, v59
	v_fma_f32 v52, v62, v52, v58
	v_fma_f32 v52, v61, v52, v57
	v_fma_f32 v52, v60, v52, v56
	ds_bpermute_b32 v87, v128, v52
	s_waitcnt lgkmcnt(1)
	v_mul_f32_e32 v83, v53, v83
	s_waitcnt lgkmcnt(0)
	v_fma_f32 v87, v53, v87, v52
	v_cndmask_b32_e64 v52, v87, v52, s[40:41]
	v_cndmask_b32_e64 v53, v83, v53, s[40:41]
	ds_bpermute_b32 v83, v129, v53
	ds_bpermute_b32 v87, v129, v52
	s_waitcnt lgkmcnt(1)
	v_mul_f32_e32 v83, v53, v83
	s_waitcnt lgkmcnt(0)
	v_fma_f32 v87, v53, v87, v52
	v_cndmask_b32_e64 v87, v52, v87, s[42:43]
	v_cndmask_b32_e64 v52, v53, v83, s[42:43]
	ds_bpermute_b32 v83, v130, v52
	ds_bpermute_b32 v88, v130, v87
	ds_bpermute_b32 v53, v128, v87
	v_mul_f32_e32 v87, v55, v54
	v_mul_f32_e32 v87, v78, v87
	v_mul_f32_e32 v87, v79, v87
	s_waitcnt lgkmcnt(1)
	v_fmac_f32_e32 v88, v86, v83
	v_fma_f32 v83, 0, v55, v51
	v_fma_f32 v83, v54, v83, v50
	v_fma_f32 v83, v78, v83, v49
	v_fma_f32 v83, v79, v83, v48
	ds_bpermute_b32 v89, v128, v87
	ds_bpermute_b32 v90, v128, v83
	ds_bpermute_b32 v52, v128, v52
	s_waitcnt lgkmcnt(2)
	v_mul_f32_e32 v89, v87, v89
	s_waitcnt lgkmcnt(1)
	v_fma_f32 v90, v87, v90, v83
	v_cndmask_b32_e64 v83, v90, v83, s[40:41]
	v_cndmask_b32_e64 v87, v89, v87, s[40:41]
	ds_bpermute_b32 v89, v129, v87
	ds_bpermute_b32 v90, v129, v83
	s_waitcnt lgkmcnt(1)
	v_mul_f32_e32 v89, v87, v89
	s_waitcnt lgkmcnt(0)
	v_fma_f32 v90, v87, v90, v83
	v_cndmask_b32_e64 v83, v83, v90, s[42:43]
	v_cndmask_b32_e64 v87, v87, v89, s[42:43]
	ds_bpermute_b32 v87, v128, v87
	ds_bpermute_b32 v83, v128, v83
	s_waitcnt lgkmcnt(1)
	v_cndmask_b32_e64 v87, v87, 1.0, s[40:41]
	s_waitcnt lgkmcnt(0)
	v_cndmask_b32_e64 v83, v83, 0, s[40:41]
	v_fmac_f32_e32 v83, v88, v87
	v_fmac_f32_e32 v51, v55, v83
	v_fmac_f32_e32 v50, v54, v51
	v_fmac_f32_e32 v49, v78, v50
	v_fmac_f32_e32 v48, v79, v49
	s_and_saveexec_b64 s[4:5], s[66:67]
	s_cbranch_execz .LBB0_825
	global_store_dword v[84:85], v48, off offset:2048

.LBB0_827:
	ds_read_u16 v149, v140 offset:32
	ds_read_u16 v150, v140 offset:1056
	ds_read_u16 v151, v140 offset:2080
	ds_read_u16 v152, v140 offset:3104
	ds_read_u16 v154, v140 offset:4128
	ds_read_u16 v155, v140 offset:5152
	ds_read_u16 v156, v140 offset:6176
	ds_read_u16 v159, v140 offset:19488
	ds_bpermute_b32 v120, v80, v122 offset:64
	ds_bpermute_b32 v153, v80, v114 offset:64
	v_mfma_f32_16x16x32_bf16 v[84:87], v[8:11], v[16:19], 0
	ds_bpermute_b32 v121, v80, v123 offset:64
	ds_bpermute_b32 v157, v80, v124 offset:64
	ds_bpermute_b32 v158, v80, v125 offset:64
	v_mfma_f32_16x16x32_bf16 v[104:107], v[12:15], v[20:23], v[84:87]
	s_waitcnt lgkmcnt(12)
	v_lshlrev_b32_e32 v149, 16, v149
	s_waitcnt lgkmcnt(11)
	v_lshlrev_b32_e32 v150, 16, v150
	s_waitcnt lgkmcnt(3)
	v_fma_f32 v149, v120, v149, v153
	v_mfma_f32_16x16x32_bf16 v[84:87], v[8:11], v[24:27], 0
	v_lshlrev_b32_e32 v151, 16, v151
	s_waitcnt lgkmcnt(2)
	v_fmac_f32_e32 v149, v121, v150
	v_fma_f32 v150, v120, v150, v153
	v_lshlrev_b32_e32 v152, 16, v152
	s_waitcnt lgkmcnt(1)
	v_fmac_f32_e32 v149, v157, v151
	v_fmac_f32_e32 v150, v121, v151
	v_fma_f32 v151, v120, v151, v153
	v_mfma_f32_16x16x32_bf16 v[108:111], v[12:15], v[28:31], v[84:87]
	v_lshlrev_b32_e32 v154, 16, v154
	s_waitcnt lgkmcnt(0)
	v_fmac_f32_e32 v149, v158, v152
	v_fmac_f32_e32 v150, v157, v152
	v_fmac_f32_e32 v151, v121, v152
	v_fma_f32 v152, v120, v152, v153
	v_lshlrev_b32_e32 v155, 16, v155
	v_fmac_f32_e32 v150, v158, v154
	v_fmac_f32_e32 v151, v157, v154
	v_fmac_f32_e32 v152, v121, v154
	ds_read_u16 v154, v140 offset:16416
	ds_read_u16 v160, v140 offset:20512
	ds_read_u16 v161, v140 offset:21536
	ds_read_u16 v162, v140 offset:22560
	v_lshlrev_b32_e32 v156, 16, v156
	v_fmac_f32_e32 v151, v158, v155
	v_fmac_f32_e32 v152, v157, v155
	ds_read_u16 v155, v140 offset:17440
	v_fmac_f32_e32 v152, v158, v156
	ds_read_u16 v156, v140 offset:18464
	v_mul_f32_e32 v134, 0xbfb8aa3b, v134
	v_mul_f32_e32 v135, 0xbfb8aa3b, v135
	v_fmamk_f32 v107, v107, 0xbfb8aa3b, v134
	v_fmamk_f32 v111, v111, 0xbfb8aa3b, v135
	s_waitcnt lgkmcnt(5)
	v_lshlrev_b32_e32 v154, 16, v154
	v_exp_f32_e32 v107, v107
	v_exp_f32_e32 v111, v111
	s_waitcnt lgkmcnt(1)
	v_lshlrev_b32_e32 v155, 16, v155
	v_fma_f32 v154, v120, v154, v153
	s_waitcnt lgkmcnt(0)
	v_lshlrev_b32_e32 v156, 16, v156
	v_lshlrev_b32_e32 v159, 16, v159
	v_fmac_f32_e32 v154, v121, v155
	v_fma_f32 v155, v120, v155, v153
	v_lshlrev_b32_e32 v160, 16, v160
	v_fmac_f32_e32 v154, v157, v156
	v_fmac_f32_e32 v155, v121, v156
	v_fma_f32 v156, v120, v156, v153
	v_fmac_f32_e32 v153, v120, v159
	v_lshlrev_b32_e32 v161, 16, v161
	v_fmac_f32_e32 v156, v121, v159
	v_fmac_f32_e32 v153, v121, v160
	v_add_f32_e32 v107, 1.0, v107
	v_add_f32_e32 v111, 1.0, v111
	v_fmac_f32_e32 v155, v157, v159
	v_fmac_f32_e32 v156, v157, v160
	v_fmac_f32_e32 v153, v157, v161
	v_mul_f32_e32 v157, v107, v111
	v_rcp_f32_e32 v157, v157
	v_fmamk_f32 v106, v106, 0xbfb8aa3b, v134
	v_mul_f32_e32 v111, v111, v157
	v_mul_f32_e32 v136, 0xbfb8aa3b, v136
	v_mul_f32_e32 v111, v111, v136
	v_exp_f32_e32 v111, v111
	v_mul_f32_e32 v107, v107, v157
	v_fmamk_f32 v110, v110, 0xbfb8aa3b, v135
	v_exp_f32_e32 v106, v106
	v_fma_f32 v157, -v111, v111, 1.0 clamp
	v_exp_f32_e32 v110, v110
	v_sqrt_f32_e32 v157, v157
	v_lshlrev_b32_e32 v162, 16, v162
	v_fmac_f32_e32 v153, v158, v162
	v_mul_f32_e32 v107, v107, v153
	v_add_f32_e32 v106, 1.0, v106
	v_add_f32_e32 v110, 1.0, v110
	v_mul_f32_e32 v107, v157, v107
	v_mul_f32_e32 v157, v106, v110
	v_rcp_f32_e32 v157, v157
	v_fmamk_f32 v105, v105, 0xbfb8aa3b, v134
	v_mul_f32_e32 v110, v110, v157
	v_mul_f32_e32 v110, v110, v136
	v_exp_f32_e32 v110, v110
	v_mul_f32_e32 v106, v106, v157
	v_fmamk_f32 v109, v109, 0xbfb8aa3b, v135
	v_exp_f32_e32 v105, v105
	v_fma_f32 v157, -v110, v110, 1.0 clamp
	v_exp_f32_e32 v109, v109
	v_sqrt_f32_e32 v157, v157
	v_fmac_f32_e32 v156, v158, v161
	v_mul_f32_e32 v106, v106, v156
	v_add_f32_e32 v105, 1.0, v105
	v_add_f32_e32 v109, 1.0, v109
	v_mul_f32_e32 v106, v157, v106
	v_mul_f32_e32 v157, v105, v109
	v_rcp_f32_e32 v157, v157
	v_fmamk_f32 v104, v104, 0xbfb8aa3b, v134
	v_mul_f32_e32 v109, v109, v157
	v_mul_f32_e32 v109, v109, v136
	v_mul_f32_e32 v105, v105, v157
	v_exp_f32_e32 v157, v109
	v_fmamk_f32 v108, v108, 0xbfb8aa3b, v135
	v_exp_f32_e32 v104, v104
	v_exp_f32_e32 v108, v108
	v_fma_f32 v109, -v157, v157, 1.0 clamp
	v_sqrt_f32_e32 v109, v109
	v_fmac_f32_e32 v155, v158, v160
	ds_bpermute_b32 v147, v80, v113 offset:64
	ds_bpermute_b32 v148, v80, v115 offset:64
	v_mfma_f32_16x16x32_bf16 v[80:83], v[0:3], v[16:19], 0
	v_mul_f32_e32 v105, v105, v155
	v_add_f32_e32 v104, 1.0, v104
	v_add_f32_e32 v108, 1.0, v108
	v_mul_f32_e32 v105, v109, v105
	v_mul_f32_e32 v109, v104, v108
	v_rcp_f32_e32 v109, v109
	v_mfma_f32_16x16x32_bf16 v[96:99], v[4:7], v[20:23], v[80:83]
	v_fmac_f32_e32 v154, v158, v159
	v_lshl_add_u64 v[120:121], v[118:119], 0, s[70:71]
	v_mul_f32_e32 v108, v108, v109
	v_mfma_f32_16x16x32_bf16 v[80:83], v[0:3], v[24:27], 0
	v_mul_f32_e32 v108, v108, v136
	v_exp_f32_e32 v158, v108
	v_mfma_f32_16x16x32_bf16 v[100:103], v[4:7], v[28:31], v[80:83]
	s_nop 0
	v_fmamk_f32 v99, v99, 0xbfb8aa3b, v134
	v_fma_f32 v108, -v158, v158, 1.0 clamp
	v_exp_f32_e32 v99, v99
	s_nop 2
	s_nop 1
	v_fmamk_f32 v103, v103, 0xbfb8aa3b, v135
	s_nop 0
	v_exp_f32_e32 v103, v103
	v_sqrt_f32_e32 v108, v108
	v_mul_f32_e32 v104, v104, v109
	v_mul_f32_e32 v104, v104, v154
	v_add_f32_e32 v99, 1.0, v99
	v_add_f32_e32 v103, 1.0, v103
	v_mul_f32_e32 v104, v108, v104
	v_mul_f32_e32 v108, v99, v103
	v_rcp_f32_e32 v108, v108
	v_fmamk_f32 v98, v98, 0xbfb8aa3b, v134
	v_mul_f32_e32 v99, v99, v108
	v_mul_f32_e32 v109, v99, v152
	v_mul_f32_e32 v99, v103, v108
	v_mul_f32_e32 v99, v99, v136
	v_fmamk_f32 v102, v102, 0xbfb8aa3b, v135
	v_exp_f32_e32 v98, v98
	v_exp_f32_e32 v102, v102
	v_exp_f32_e32 v99, v99
	v_add_f32_e32 v98, 1.0, v98
	v_add_f32_e32 v102, 1.0, v102
	v_fma_f32 v103, -v99, v99, 1.0 clamp
	v_mul_f32_e32 v108, v98, v102
	v_fmamk_f32 v97, v97, 0xbfb8aa3b, v134
	v_fmamk_f32 v101, v101, 0xbfb8aa3b, v135
	v_rcp_f32_e32 v108, v108
	v_exp_f32_e32 v97, v97
	v_exp_f32_e32 v101, v101
	v_sqrt_f32_e32 v103, v103
	v_mul_f32_e32 v98, v98, v108
	v_add_f32_e32 v97, 1.0, v97
	v_add_f32_e32 v101, 1.0, v101
	v_mul_f32_e32 v103, v103, v109
	v_mul_f32_e32 v109, v98, v151
	v_mul_f32_e32 v98, v102, v108
	v_mul_f32_e32 v108, v97, v101
	v_rcp_f32_e32 v108, v108
	v_mul_f32_e32 v98, v98, v136
	v_mul_f32_e32 v101, v101, v108
	v_mul_f32_e32 v101, v101, v136
	v_exp_f32_e32 v101, v101
	v_mul_f32_e32 v97, v97, v108
	v_fmamk_f32 v96, v96, 0xbfb8aa3b, v134
	v_fmamk_f32 v100, v100, 0xbfb8aa3b, v135
	v_fma_f32 v108, -v101, v101, 1.0 clamp
	v_exp_f32_e32 v96, v96
	v_exp_f32_e32 v100, v100
	v_exp_f32_e32 v98, v98
	v_sqrt_f32_e32 v108, v108
	v_mul_f32_e32 v97, v97, v150
	v_add_f32_e32 v96, 1.0, v96
	v_add_f32_e32 v100, 1.0, v100
	v_fma_f32 v102, -v98, v98, 1.0 clamp
	v_mul_f32_e32 v97, v108, v97
	v_mul_f32_e32 v108, v96, v100
	v_rcp_f32_e32 v108, v108
	v_sqrt_f32_e32 v102, v102
	v_mfma_f32_16x16x32_bf16 v[80:83], v[0:3], v[32:35], 0
	v_mul_f32_e32 v96, v96, v108
	v_mul_f32_e32 v102, v102, v109
	v_mul_f32_e32 v109, v96, v149
	v_mul_f32_e32 v96, v100, v108
	v_mul_f32_e32 v96, v96, v136
	v_exp_f32_e32 v96, v96
	v_mfma_f32_16x16x32_bf16 v[88:91], v[8:11], v[32:35], 0
	v_fma_f32 v100, -v96, v96, 1.0 clamp
	v_sqrt_f32_e32 v100, v100
	v_mfma_f32_16x16x32_bf16 v[84:87], v[4:7], v[36:39], v[80:83]
	v_mul_f32_e32 v100, v100, v109
	v_fma_f32 v108, 0, v96, v100
	v_fma_f32 v108, v101, v108, v97
	v_mul_f32_e32 v109, v96, v101
	v_fma_f32 v108, v98, v108, v102
	v_mul_f32_e32 v109, v98, v109
	v_fma_f32 v108, v99, v108, v103
	v_mul_f32_e32 v109, v99, v109
	ds_bpermute_b32 v159, v131, v109
	ds_bpermute_b32 v160, v131, v108
	v_mfma_f32_16x16x32_bf16 v[92:95], v[12:15], v[36:39], v[88:91]
	s_waitcnt lgkmcnt(1)
	v_mul_f32_e32 v159, v109, v159
	s_waitcnt lgkmcnt(0)
	v_fma_f32 v160, v109, v160, v108
	v_cndmask_b32_e64 v108, v160, v108, s[44:45]
	v_cndmask_b32_e64 v109, v159, v109, s[44:45]
	ds_bpermute_b32 v159, v129, v109
	ds_bpermute_b32 v160, v129, v108
	v_mfma_f32_16x16x32_bf16 v[80:83], v[0:3], v[40:43], 0
	s_waitcnt lgkmcnt(1)
	v_mul_f32_e32 v159, v109, v159
	s_waitcnt lgkmcnt(0)
	v_fma_f32 v160, v109, v160, v108
	v_cndmask_b32_e64 v160, v108, v160, s[46:47]
	v_cndmask_b32_e64 v108, v109, v159, s[46:47]
	ds_bpermute_b32 v159, v132, v108
	ds_bpermute_b32 v161, v132, v160
	ds_bpermute_b32 v109, v131, v160
	v_mul_f32_e32 v160, v158, v157
	v_mul_f32_e32 v160, v110, v160
	v_mul_f32_e32 v160, v111, v160
	s_waitcnt lgkmcnt(1)
	v_fmac_f32_e32 v161, v147, v159
	v_fma_f32 v159, 0, v158, v104
	v_fma_f32 v159, v157, v159, v105
	v_fma_f32 v159, v110, v159, v106
	v_fma_f32 v159, v111, v159, v107
	ds_bpermute_b32 v162, v131, v160
	ds_bpermute_b32 v163, v131, v159
	v_mfma_f32_16x16x32_bf16 v[88:91], v[8:11], v[40:43], 0
	ds_bpermute_b32 v108, v131, v108
	s_waitcnt lgkmcnt(2)
	v_mul_f32_e32 v162, v160, v162
	s_waitcnt lgkmcnt(1)
	v_fma_f32 v163, v160, v163, v159
	v_cndmask_b32_e64 v159, v163, v159, s[44:45]
	v_cndmask_b32_e64 v160, v162, v160, s[44:45]
	ds_bpermute_b32 v162, v129, v160
	ds_bpermute_b32 v163, v129, v159
	v_mfma_f32_16x16x32_bf16 v[80:83], v[4:7], v[44:47], v[80:83]
	s_waitcnt lgkmcnt(1)
	v_mul_f32_e32 v162, v160, v162
	s_waitcnt lgkmcnt(0)
	v_fma_f32 v163, v160, v163, v159
	v_cndmask_b32_e64 v159, v159, v163, s[46:47]
	v_cndmask_b32_e64 v160, v160, v162, s[46:47]
	ds_bpermute_b32 v160, v131, v160
	ds_bpermute_b32 v159, v131, v159
	v_mfma_f32_16x16x32_bf16 v[88:91], v[12:15], v[44:47], v[88:91]
	s_waitcnt lgkmcnt(1)
	v_cndmask_b32_e64 v160, v160, 1.0, s[44:45]
	s_waitcnt lgkmcnt(0)
	v_cndmask_b32_e64 v159, v159, 0, s[44:45]
	v_fmac_f32_e32 v159, v161, v160
	v_fmac_f32_e32 v104, v158, v159
	v_fmac_f32_e32 v105, v157, v104
	v_fmac_f32_e32 v106, v110, v105
	v_fmac_f32_e32 v107, v111, v106
	s_and_saveexec_b64 s[4:5], s[68:69]
	s_cbranch_execz .LBB0_829
	v_add_co_u32_e32 v110, vcc, 0x6000000, v120
	s_nop 1
	v_addc_co_u32_e32 v111, vcc, 0, v121, vcc
	global_store_dword v[110:111], v107, off offset:64
.LBB0_829:
	s_or_b64 exec, exec, s[4:5]
	v_mul_f32_e32 v137, 0xbfb8aa3b, v137
	v_mul_f32_e32 v138, 0xbfb8aa3b, v138
	v_fmamk_f32 v95, v95, 0xbfb8aa3b, v137
	v_fmamk_f32 v91, v91, 0xbfb8aa3b, v138
	v_exp_f32_e32 v95, v95
	v_exp_f32_e32 v91, v91
	v_add_f32_e32 v95, 1.0, v95
	v_add_f32_e32 v91, 1.0, v91
	v_fmamk_f32 v94, v94, 0xbfb8aa3b, v137
	v_fmamk_f32 v90, v90, 0xbfb8aa3b, v138
	v_mul_f32_e32 v110, v95, v91
	v_exp_f32_e32 v94, v94
	v_exp_f32_e32 v90, v90
	v_rcp_f32_e32 v110, v110
	v_add_f32_e32 v94, 1.0, v94
	v_add_f32_e32 v90, 1.0, v90
	v_fmamk_f32 v93, v93, 0xbfb8aa3b, v137
	v_fmamk_f32 v89, v89, 0xbfb8aa3b, v138
	v_mul_f32_e32 v95, v95, v110
	v_mul_f32_e32 v91, v91, v110
	v_mul_f32_e32 v110, v94, v90
	v_exp_f32_e32 v93, v93
	v_exp_f32_e32 v89, v89
	v_rcp_f32_e32 v110, v110
	v_add_f32_e32 v93, 1.0, v93
	v_add_f32_e32 v89, 1.0, v89
	v_fmamk_f32 v92, v92, 0xbfb8aa3b, v137
	v_fmamk_f32 v88, v88, 0xbfb8aa3b, v138
	v_mul_f32_e32 v94, v94, v110
	v_mul_f32_e32 v90, v90, v110
	v_mul_f32_e32 v110, v93, v89
	v_exp_f32_e32 v92, v92
	v_exp_f32_e32 v88, v88
	v_rcp_f32_e32 v110, v110
	v_add_f32_e32 v92, 1.0, v92
	v_add_f32_e32 v88, 1.0, v88
	v_fmamk_f32 v87, v87, 0xbfb8aa3b, v137
	v_fmamk_f32 v83, v83, 0xbfb8aa3b, v138
	v_mul_f32_e32 v93, v93, v110
	v_mul_f32_e32 v89, v89, v110
	v_mul_f32_e32 v110, v92, v88
	v_exp_f32_e32 v87, v87
	v_exp_f32_e32 v83, v83
	v_rcp_f32_e32 v110, v110
	v_add_f32_e32 v87, 1.0, v87
	v_add_f32_e32 v83, 1.0, v83
	v_mul_f32_e32 v92, v92, v110
	v_mul_f32_e32 v88, v88, v110
	v_mul_f32_e32 v110, v87, v83
	v_rcp_f32_e32 v110, v110
	v_fmamk_f32 v86, v86, 0xbfb8aa3b, v137
	v_fmamk_f32 v82, v82, 0xbfb8aa3b, v138
	v_mul_f32_e32 v83, v83, v110
	v_mul_f32_e32 v139, 0xbfb8aa3b, v139
	v_mul_f32_e32 v83, v83, v139
	v_mul_f32_e32 v87, v87, v110
	v_exp_f32_e32 v110, v83
	v_exp_f32_e32 v86, v86
	v_exp_f32_e32 v82, v82
	v_mul_f32_e32 v87, v87, v152
	v_fma_f32 v83, -v110, v110, 1.0 clamp
	v_sqrt_f32_e32 v83, v83
	v_add_f32_e32 v86, 1.0, v86
	v_add_f32_e32 v82, 1.0, v82
	v_mul_f32_e32 v91, v91, v139
	v_mul_f32_e32 v83, v87, v83
	v_mul_f32_e32 v87, v86, v82
	v_rcp_f32_e32 v87, v87
	v_mul_f32_e32 v111, v95, v153
	v_exp_f32_e32 v95, v91
	v_mul_f32_e32 v82, v82, v87
	v_mul_f32_e32 v82, v82, v139
	v_fma_f32 v91, -v95, v95, 1.0 clamp
	v_mul_f32_e32 v86, v86, v87
	v_exp_f32_e32 v87, v82
	v_sqrt_f32_e32 v91, v91
	v_mul_f32_e32 v90, v90, v139
	v_fma_f32 v82, -v87, v87, 1.0 clamp
	v_fmamk_f32 v85, v85, 0xbfb8aa3b, v137
	v_fmamk_f32 v81, v81, 0xbfb8aa3b, v138
	v_exp_f32_e32 v85, v85
	v_exp_f32_e32 v81, v81
	v_mul_f32_e32 v91, v91, v111
	v_mul_f32_e32 v111, v94, v156
	v_exp_f32_e32 v94, v90
	v_sqrt_f32_e32 v82, v82
	v_mul_f32_e32 v86, v86, v151
	v_add_f32_e32 v85, 1.0, v85
	v_add_f32_e32 v81, 1.0, v81
	v_fma_f32 v90, -v94, v94, 1.0 clamp
	v_mul_f32_e32 v82, v86, v82
	v_mul_f32_e32 v86, v85, v81
	v_rcp_f32_e32 v86, v86
	v_sqrt_f32_e32 v90, v90
	v_mul_f32_e32 v89, v89, v139
	v_mul_f32_e32 v81, v81, v86
	v_mul_f32_e32 v90, v90, v111
	v_mul_f32_e32 v111, v93, v155
	v_exp_f32_e32 v93, v89
	v_mul_f32_e32 v81, v81, v139
	v_mul_f32_e32 v85, v85, v86
	v_exp_f32_e32 v86, v81
	v_fma_f32 v89, -v93, v93, 1.0 clamp
	v_sqrt_f32_e32 v89, v89
	v_fma_f32 v81, -v86, v86, 1.0 clamp
	v_fmamk_f32 v84, v84, 0xbfb8aa3b, v137
	v_fmamk_f32 v80, v80, 0xbfb8aa3b, v138
	v_exp_f32_e32 v84, v84
	v_exp_f32_e32 v80, v80
	v_mul_f32_e32 v88, v88, v139
	v_sqrt_f32_e32 v81, v81
	v_mul_f32_e32 v89, v89, v111
	v_mul_f32_e32 v111, v92, v154
	v_exp_f32_e32 v92, v88
	v_mul_f32_e32 v85, v85, v150
	v_add_f32_e32 v84, 1.0, v84
	v_add_f32_e32 v80, 1.0, v80
	v_mul_f32_e32 v81, v85, v81
	v_mul_f32_e32 v85, v84, v80
	v_rcp_f32_e32 v85, v85
	v_fma_f32 v88, -v92, v92, 1.0 clamp
	v_sqrt_f32_e32 v88, v88
	v_mul_f32_e32 v80, v80, v85
	v_mul_f32_e32 v80, v80, v139
	v_mul_f32_e32 v88, v88, v111
	v_exp_f32_e32 v111, v80
	v_mul_f32_e32 v84, v84, v85
	v_mul_f32_e32 v84, v84, v149
	v_mul_f32_e32 v85, v95, v94
	v_fma_f32 v80, -v111, v111, 1.0 clamp
	v_sqrt_f32_e32 v80, v80
	v_mul_f32_e32 v85, v93, v85
	v_mul_f32_e32 v85, v92, v85
	ds_bpermute_b32 v149, v128, v85
	v_mul_f32_e32 v80, v84, v80
	v_fma_f32 v84, 0, v95, v91
	v_fma_f32 v84, v94, v84, v90
	v_fma_f32 v84, v93, v84, v89
	v_fma_f32 v84, v92, v84, v88
	ds_bpermute_b32 v150, v128, v84
	s_waitcnt lgkmcnt(1)
	v_mul_f32_e32 v149, v85, v149
	s_waitcnt lgkmcnt(0)
	v_fma_f32 v150, v85, v150, v84
	v_cndmask_b32_e64 v84, v150, v84, s[40:41]
	v_cndmask_b32_e64 v85, v149, v85, s[40:41]
	ds_bpermute_b32 v149, v129, v85
	ds_bpermute_b32 v150, v129, v84
	s_waitcnt lgkmcnt(1)
	v_mul_f32_e32 v149, v85, v149
	s_waitcnt lgkmcnt(0)
	v_fma_f32 v150, v85, v150, v84
	v_cndmask_b32_e64 v150, v84, v150, s[42:43]
	v_cndmask_b32_e64 v84, v85, v149, s[42:43]
	ds_bpermute_b32 v149, v130, v84
	ds_bpermute_b32 v151, v130, v150
	ds_bpermute_b32 v85, v128, v150
	v_mul_f32_e32 v150, v110, v87
	v_mul_f32_e32 v150, v86, v150
	v_mul_f32_e32 v150, v111, v150
	s_waitcnt lgkmcnt(1)
	v_fmac_f32_e32 v151, v148, v149
	v_fma_f32 v149, 0, v110, v83
	v_fma_f32 v149, v87, v149, v82
	v_fma_f32 v149, v86, v149, v81
	v_fma_f32 v149, v111, v149, v80
	ds_bpermute_b32 v152, v128, v150
	ds_bpermute_b32 v153, v128, v149
	ds_bpermute_b32 v84, v128, v84
	s_waitcnt lgkmcnt(2)
	v_mul_f32_e32 v152, v150, v152
	s_waitcnt lgkmcnt(1)
	v_fma_f32 v153, v150, v153, v149
	v_cndmask_b32_e64 v149, v153, v149, s[40:41]
	v_cndmask_b32_e64 v150, v152, v150, s[40:41]
	ds_bpermute_b32 v152, v129, v150
	ds_bpermute_b32 v153, v129, v149
	s_waitcnt lgkmcnt(1)
	v_mul_f32_e32 v152, v150, v152
	s_waitcnt lgkmcnt(0)
	v_fma_f32 v153, v150, v153, v149
	v_cndmask_b32_e64 v149, v149, v153, s[42:43]
	v_cndmask_b32_e64 v150, v150, v152, s[42:43]
	ds_bpermute_b32 v150, v128, v150
	ds_bpermute_b32 v149, v128, v149
	s_waitcnt lgkmcnt(1)
	v_cndmask_b32_e64 v150, v150, 1.0, s[40:41]
	s_waitcnt lgkmcnt(0)
	v_cndmask_b32_e64 v149, v149, 0, s[40:41]
	v_fmac_f32_e32 v149, v151, v150
	v_fmac_f32_e32 v83, v110, v149
	v_fmac_f32_e32 v82, v87, v83
	v_fmac_f32_e32 v81, v86, v82
	v_fmac_f32_e32 v80, v111, v81
	s_and_saveexec_b64 s[4:5], s[66:67]
	s_cbranch_execz .LBB0_831
	v_add_co_u32_e32 v86, vcc, 0x6000000, v120
	s_nop 1
	v_addc_co_u32_e32 v87, vcc, 0, v121, vcc
	global_store_dword v[86:87], v80, off offset:2112
